# speedup vs baseline: 1.0316x; 1.0047x over previous
; #define DECODE(Lx, PM, PN) do { int wgid = (Lx); \
;     { int q = nwg / NXCD, r = nwg % NXCD, xcd = wgid % NXCD, off = wgid / NXCD; wgid = (xcd < r ? xcd * (q + 1) : r * (q + 1) + (xcd - r) * q) + off; } \
;     const int nig = WGM * nN, gid = wgid / nig, fm = gid * WGM, gsz = min(nM - fm, WGM); \
;     PM = fm + ((wgid % nig) % gsz); PN = (wgid % nig) / gsz; } while (0)
; template <int MODE>
; DEV void gemm_phase(const bf16_t* __restrict__ A, const bf16_t* __restrict__ Bt, int M, int N, int K, bf16_t* __restrict__ Out, int ldo,
;                     const float* __restrict__ rstd, const float* __restrict__ rope) {
;     ...
;     const bool has_next = (L + (int)gridDim.x) < nwg;
;     int npm = pm, npn = pn; if (has_next) DECODE(L + (int)gridDim.x, npm, npn);
;     const char* nA = (const char*)A + (size_t)npm * tstep; const char* nB = (const char*)Bt + (size_t)npn * tstep;
;     const int brow = pm * BM, bcol = pn * BM;
;     ...
; #pragma unroll
;     for (int a = 0; a < 2; ++a)
; #pragma unroll
;       for (int b = 0; b < 2; ++b)
; #pragma unroll
;         for (int m = 0; m < 4; ++m)
; #pragma unroll
;           for (int n = 0; n < 2; ++n) acc[a][b][m][n] = (f32x4){0.f, 0.f, 0.f, 0.f};
;     pm = npm; pn = npn; cA = nA; cB = nB; L += (int)gridDim.x;
.LBB0_127:
	s_ashr_i32 s19, s18, 31
	s_lshl_b64 s[22:23], s[18:19], 20
	s_add_u32 s19, s66, s22
	s_addc_u32 s42, s67, s23
	s_ashr_i32 s21, s20, 31
	s_lshl_b64 s[24:25], s[20:21], 20
	s_add_u32 s21, s58, s24
	s_addc_u32 s43, s59, s25
	s_add_u32 s44, s58, s26
	s_addc_u32 s45, s59, s27
	v_readlane_b32 s28, v254, 63
	s_add_u32 s46, s28, s8
	v_readlane_b32 s8, v255, 0
	v_mov_b32_e32 v0, 0
	s_addc_u32 s47, s8, s9
	s_mov_b32 s48, -2
	s_mov_b64 s[8:9], 0
	v_mov_b32_e32 v1, v0
	v_mov_b32_e32 v2, v0
	v_mov_b32_e32 v3, v0
	v_mov_b32_e32 v4, v0
	v_mov_b32_e32 v5, v0
	v_mov_b32_e32 v6, v0
	v_mov_b32_e32 v7, v0
	s_waitcnt vmcnt(0)
	v_mov_b32_e32 v16, v0
	v_mov_b32_e32 v17, v0
	v_mov_b32_e32 v18, v0
	v_mov_b32_e32 v19, v0
	v_mov_b32_e32 v20, v0
	v_mov_b32_e32 v21, v0
	v_mov_b32_e32 v22, v0
	v_mov_b32_e32 v23, v0
	v_mov_b32_e32 v32, v0
	s_waitcnt lgkmcnt(0)
	v_mov_b32_e32 v33, v0
	v_mov_b32_e32 v34, v0
	v_mov_b32_e32 v35, v0
	v_mov_b32_e32 v36, v0
	v_mov_b32_e32 v37, v0
	v_mov_b32_e32 v38, v0
	v_mov_b32_e32 v39, v0
	v_mov_b32_e32 v48, v0
	v_mov_b32_e32 v49, v0
	v_mov_b32_e32 v50, v0
	v_mov_b32_e32 v51, v0
	v_mov_b32_e32 v52, v0
	v_mov_b32_e32 v53, v0
	v_mov_b32_e32 v54, v0
	v_mov_b32_e32 v55, v0
	v_mov_b32_e32 v8, v0
	v_mov_b32_e32 v9, v0
	v_mov_b32_e32 v10, v0
	v_mov_b32_e32 v11, v0
	v_mov_b32_e32 v12, v0
	v_mov_b32_e32 v13, v0
	v_mov_b32_e32 v14, v0
	v_mov_b32_e32 v15, v0
	v_mov_b32_e32 v24, v0
	v_mov_b32_e32 v25, v0
	v_mov_b32_e32 v26, v0
	v_mov_b32_e32 v27, v0
	v_mov_b32_e32 v28, v0
	v_mov_b32_e32 v29, v0
	v_mov_b32_e32 v30, v0
	v_mov_b32_e32 v31, v0
	v_mov_b32_e32 v40, v0
	v_mov_b32_e32 v41, v0
	v_mov_b32_e32 v42, v0
	v_mov_b32_e32 v43, v0
	v_mov_b32_e32 v44, v0
	v_mov_b32_e32 v45, v0
	v_mov_b32_e32 v46, v0
	v_mov_b32_e32 v47, v0
	v_mov_b32_e32 v56, v0
	v_mov_b32_e32 v57, v0
	v_mov_b32_e32 v58, v0
	v_mov_b32_e32 v59, v0
	v_mov_b32_e32 v60, v0
	v_mov_b32_e32 v61, v0
	v_mov_b32_e32 v62, v0
	v_mov_b32_e32 v63, v0
	v_mov_b32_e32 v64, v0
	v_mov_b32_e32 v65, v0
	v_mov_b32_e32 v66, v0
	v_mov_b32_e32 v67, v0
	v_mov_b32_e32 v68, v0
	v_mov_b32_e32 v69, v0
	v_mov_b32_e32 v70, v0
	v_mov_b32_e32 v71, v0
	v_mov_b32_e32 v80, v0
	v_mov_b32_e32 v81, v0
	v_mov_b32_e32 v82, v0
	v_mov_b32_e32 v83, v0
	v_mov_b32_e32 v84, v0
	v_mov_b32_e32 v85, v0
	v_mov_b32_e32 v86, v0
	v_mov_b32_e32 v87, v0
	v_mov_b32_e32 v96, v0
	v_mov_b32_e32 v97, v0
	v_mov_b32_e32 v98, v0
	v_mov_b32_e32 v99, v0
	v_mov_b32_e32 v100, v0
	v_mov_b32_e32 v101, v0
	v_mov_b32_e32 v102, v0
	v_mov_b32_e32 v103, v0
	v_mov_b32_e32 v112, v0
	v_mov_b32_e32 v113, v0
	v_mov_b32_e32 v114, v0
	v_mov_b32_e32 v115, v0
	v_mov_b32_e32 v116, v0
	v_mov_b32_e32 v117, v0
	v_mov_b32_e32 v118, v0
	v_mov_b32_e32 v119, v0
	v_mov_b32_e32 v72, v0
	v_mov_b32_e32 v73, v0
	v_mov_b32_e32 v74, v0
	v_mov_b32_e32 v75, v0
	v_mov_b32_e32 v76, v0
	v_mov_b32_e32 v77, v0
	v_mov_b32_e32 v78, v0
	v_mov_b32_e32 v79, v0
	v_mov_b32_e32 v88, v0
	v_mov_b32_e32 v89, v0
	v_mov_b32_e32 v90, v0
	v_mov_b32_e32 v91, v0
	v_mov_b32_e32 v92, v0
	v_mov_b32_e32 v93, v0
	v_mov_b32_e32 v94, v0
	v_mov_b32_e32 v95, v0
	v_mov_b32_e32 v104, v0
	v_mov_b32_e32 v105, v0
	v_mov_b32_e32 v106, v0
	v_mov_b32_e32 v107, v0
	v_mov_b32_e32 v108, v0
	v_mov_b32_e32 v109, v0
	v_mov_b32_e32 v110, v0
	v_mov_b32_e32 v111, v0
	v_mov_b32_e32 v120, v0
	v_mov_b32_e32 v121, v0
	v_mov_b32_e32 v122, v0
	v_mov_b32_e32 v123, v0
	v_mov_b32_e32 v124, v0
	v_mov_b32_e32 v125, v0
	v_mov_b32_e32 v126, v0
	v_mov_b32_e32 v127, v0
	v_lshl_add_u64 v[128:129], v[160:161], 0, s[26:27]
	v_lshl_add_u64 v[130:131], v[162:163], 0, s[26:27]
	s_mov_b64 s[88:89], 0x80
	.p2align 6

; DEV void diff16_pass(const bf16_t* __restrict__ proj, int qcol, int kcol, int vcol, int q0, f32x4 (&o)[2][8], f32x4 (&l_out)[2], unsigned char* lds) {
;     ...
;   for (int j = 1; j < NT; j += 2) {
;     HALF16(SB2, alB, rfB, SA, alA, rfA, j);
;     if (j + 1 >= NT) break;
;     HALF16(SA, alA, rfA, SB2, alB, rfB, j + 1);
;   }
.LBB0_368:
	s_and_b64 vcc, exec, s[0:1]
	s_mov_b32 s23, s21
	s_cbranch_vccnz .LBB0_392
	.p2align 6

; DEV void diff16_pass(const bf16_t* __restrict__ proj, int qcol, int kcol, int vcol, int q0, f32x4 (&o)[2][8], f32x4 (&l_out)[2], unsigned char* lds) {
;     ...
;   for (int j = 1; j < NT; j += 2) {
;     HALF16(SB2, alB, rfB, SA, alA, rfA, j);
;     if (j + 1 >= NT) break;
;     HALF16(SA, alA, rfA, SB2, alB, rfB, j + 1);
;   }
.LBB0_395:
	s_and_b64 vcc, exec, s[0:1]
	s_mov_b32 s19, s17
	s_cbranch_vccnz .LBB0_419
	.p2align 6

; #define SUMPACK16(S, al) do { _Pragma("unroll") for (int g = 0; g < 2; ++g) { pa[g][0] = PKS(S, g, 0); pa[g][1] = PKS(S, g, 1); } } while (0)
; #define PVL() do { ol[0] = MF16(pa[0][0], ones, ol[0]); ol[1] = MF16(pa[1][0], ones, ol[1]); ol[0] = MF16(pa[0][1], ones, ol[0]); ol[1] = MF16(pa[1][1], ones, ol[1]); } while (0)
; DEV void diff16_pass(const bf16_t* __restrict__ proj, int qcol, int kcol, int vcol, int q0, f32x4 (&o)[2][8], f32x4 (&l_out)[2], unsigned char* lds) {
;     ...
;   { SUMPACK16(SB2, alB); DRESC16(alB, rfB); PVL(); const lds_cptr vE_ = vrdE + ((NT - 1) & 3) * D_VSLOT, vO_ = vrdO + ((NT - 1) & 3) * D_VSLOT;
;     PV16(0, vE_, vO_); PV16(1, vE_, vO_); PV16(2, vE_, vO_); PV16(3, vE_, vO_); PV16(4, vE_, vO_); PV16(5, vE_, vO_); PV16(6, vE_, vO_); PV16(7, vE_, vO_); }
.LBB0_420:
	v_cvt_pk_bf16_f32 v72, v162, v163
	v_cvt_pk_bf16_f32 v73, v161, v160
	v_cvt_pk_bf16_f32 v74, v167, v166
	v_cvt_pk_bf16_f32 v75, v164, v165
	v_cvt_pk_bf16_f32 v80, v175, v174
	v_cvt_pk_bf16_f32 v81, v172, v173
	v_cvt_pk_bf16_f32 v82, v183, v182
	v_cvt_pk_bf16_f32 v83, v181, v180
	s_mov_b32 s82, s80
	s_mov_b32 s83, s80
	s_mov_b32 s81, s80
	v_mov_b64_e32 v[94:95], s[82:83]
	v_cvt_pk_bf16_f32 v76, v171, v170
	v_cvt_pk_bf16_f32 v77, v169, v168
	v_cvt_pk_bf16_f32 v78, v178, v179
	v_cvt_pk_bf16_f32 v79, v177, v176
	v_cvt_pk_bf16_f32 v84, v186, v187
	v_cvt_pk_bf16_f32 v85, v185, v184
	v_cvt_pk_bf16_f32 v86, v191, v190
	v_cvt_pk_bf16_f32 v87, v189, v188
	v_mov_b64_e32 v[92:93], s[80:81]
	s_movk_i32 s0, 0x2200
	s_brev_b32 s4, 60
	v_mfma_f32_16x16x32_bf16 v[68:71], v[72:75], v[92:95], v[68:71]
	v_mfma_f32_16x16x32_bf16 v[56:59], v[80:83], v[92:95], v[56:59]
	v_mfma_f32_16x16x32_bf16 v[88:91], v[76:79], v[92:95], v[68:71]
	v_mfma_f32_16x16x32_bf16 v[68:71], v[84:87], v[92:95], v[56:59]
	s_nop 5
	ds_read_b64_tr_b16 v[56:57], v223 offset:49152
	ds_read_b64_tr_b16 v[58:59], v223 offset:53248
	ds_read_b64_tr_b16 v[92:93], v223 offset:57344
	ds_read_b64_tr_b16 v[94:95], v223 offset:61440
	s_waitcnt lgkmcnt(0)
	v_mfma_f32_16x16x32_bf16 v[60:63], v[72:75], v[56:59], v[60:63]
	v_mfma_f32_16x16x32_bf16 v[56:59], v[80:83], v[56:59], v[64:67]
	v_mfma_f32_16x16x32_bf16 v[60:63], v[76:79], v[92:95], v[60:63]
	v_mfma_f32_16x16x32_bf16 v[56:59], v[84:87], v[92:95], v[56:59]
	s_nop 0
	ds_read_b64_tr_b16 v[64:65], v224 offset:49152
	ds_read_b64_tr_b16 v[66:67], v224 offset:53248
	ds_read_b64_tr_b16 v[92:93], v224 offset:57344
	ds_read_b64_tr_b16 v[94:95], v224 offset:61440
	s_waitcnt lgkmcnt(0)
	v_mfma_f32_16x16x32_bf16 v[52:55], v[72:75], v[64:67], v[52:55]
	v_mfma_f32_16x16x32_bf16 v[48:51], v[80:83], v[64:67], v[48:51]
	v_mfma_f32_16x16x32_bf16 v[52:55], v[76:79], v[92:95], v[52:55]
	v_mfma_f32_16x16x32_bf16 v[48:51], v[84:87], v[92:95], v[48:51]
	ds_read_b64_tr_b16 v[64:65], v223 offset:50176
	ds_read_b64_tr_b16 v[66:67], v223 offset:54272
	ds_read_b64_tr_b16 v[92:93], v223 offset:58368
	ds_read_b64_tr_b16 v[94:95], v223 offset:62464
	s_waitcnt lgkmcnt(0)
	v_mfma_f32_16x16x32_bf16 v[44:47], v[72:75], v[64:67], v[44:47]
	v_mfma_f32_16x16x32_bf16 v[40:43], v[80:83], v[64:67], v[40:43]
	v_mfma_f32_16x16x32_bf16 v[44:47], v[76:79], v[92:95], v[44:47]
	v_mfma_f32_16x16x32_bf16 v[40:43], v[84:87], v[92:95], v[40:43]
	ds_read_b64_tr_b16 v[64:65], v224 offset:50176
	ds_read_b64_tr_b16 v[66:67], v224 offset:54272
	ds_read_b64_tr_b16 v[92:93], v224 offset:58368
	ds_read_b64_tr_b16 v[94:95], v224 offset:62464
	s_waitcnt lgkmcnt(0)
	v_mfma_f32_16x16x32_bf16 v[32:35], v[72:75], v[64:67], v[32:35]
	v_mfma_f32_16x16x32_bf16 v[64:67], v[80:83], v[64:67], v[36:39]
	v_mfma_f32_16x16x32_bf16 v[36:39], v[76:79], v[92:95], v[32:35]
	v_mfma_f32_16x16x32_bf16 v[32:35], v[84:87], v[92:95], v[64:67]
	s_nop 5
	ds_read_b64_tr_b16 v[64:65], v223 offset:51200
	ds_read_b64_tr_b16 v[66:67], v223 offset:55296
	ds_read_b64_tr_b16 v[92:93], v223 offset:59392
	ds_read_b64_tr_b16 v[94:95], v223 offset:63488
	s_waitcnt lgkmcnt(0)
	v_mfma_f32_16x16x32_bf16 v[20:23], v[72:75], v[64:67], v[20:23]
	v_mfma_f32_16x16x32_bf16 v[16:19], v[80:83], v[64:67], v[16:19]
	v_mfma_f32_16x16x32_bf16 v[64:67], v[76:79], v[92:95], v[20:23]
	v_mfma_f32_16x16x32_bf16 v[16:19], v[84:87], v[92:95], v[16:19]
	s_nop 4
	ds_read_b64_tr_b16 v[20:21], v224 offset:51200
	ds_read_b64_tr_b16 v[22:23], v224 offset:55296
	ds_read_b64_tr_b16 v[92:93], v224 offset:59392
	ds_read_b64_tr_b16 v[94:95], v224 offset:63488
	s_waitcnt lgkmcnt(0)
	v_mfma_f32_16x16x32_bf16 v[28:31], v[72:75], v[20:23], v[28:31]
	v_mfma_f32_16x16x32_bf16 v[20:23], v[80:83], v[20:23], v[24:27]
	v_mfma_f32_16x16x32_bf16 v[24:27], v[76:79], v[92:95], v[28:31]
	v_mfma_f32_16x16x32_bf16 v[20:23], v[84:87], v[92:95], v[20:23]
	s_nop 4
	ds_read_b64_tr_b16 v[28:29], v223 offset:52224
	ds_read_b64_tr_b16 v[30:31], v223 offset:56320
	ds_read_b64_tr_b16 v[92:93], v223 offset:60416
	ds_read_b64_tr_b16 v[94:95], v223 offset:64512
	s_waitcnt lgkmcnt(0)
	v_mfma_f32_16x16x32_bf16 v[12:15], v[72:75], v[28:31], v[12:15]
	v_mfma_f32_16x16x32_bf16 v[8:11], v[80:83], v[28:31], v[8:11]
	v_mfma_f32_16x16x32_bf16 v[12:15], v[76:79], v[92:95], v[12:15]
	v_mfma_f32_16x16x32_bf16 v[8:11], v[84:87], v[92:95], v[8:11]
	ds_read_b64_tr_b16 v[28:29], v224 offset:52224
	ds_read_b64_tr_b16 v[30:31], v224 offset:56320
	ds_read_b64_tr_b16 v[92:93], v224 offset:60416
	ds_read_b64_tr_b16 v[94:95], v224 offset:64512
	s_waitcnt vmcnt(0)
	s_waitcnt lgkmcnt(0)
	s_waitcnt lgkmcnt(0)
	v_mfma_f32_16x16x32_bf16 v[4:7], v[72:75], v[28:31], v[4:7]
	s_barrier
; DEV void attn_phase(const Params& p, int layer) {
;     ...
;         for (int g = 0; g < 2; ++g) { const f32x4 l4 = ld[g];
;           const f32x4 il = {__builtin_amdgcn_rcpf(l4[0]) * lam, __builtin_amdgcn_rcpf(l4[1]) * lam, __builtin_amdgcn_rcpf(l4[2]) * lam, __builtin_amdgcn_rcpf(l4[3]) * lam};
; #pragma unroll
;           for (int cb = 0; cb < 8; cb += 2) { const u32x4 w = *reinterpret_cast<const u32x4*>((const bf16_t*)o1s + (wid * 8 + g * 4 + (cb >> 1)) * 512 + lane * 8);
;             const f32x4 a4 = {__uint_as_float(w[0] << 16), __uint_as_float(w[0] & 0xffff0000u), __uint_as_float(w[1] << 16), __uint_as_float(w[1] & 0xffff0000u)};
;             const f32x4 b4 = {__uint_as_float(w[2] << 16), __uint_as_float(w[2] & 0xffff0000u), __uint_as_float(w[3] << 16), __uint_as_float(w[3] & 0xffff0000u)};
;             od[g][cb] = a4 - od[g][cb] * il; od[g][cb + 1] = b4 - od[g][cb + 1] * il; } }
	v_mfma_f32_16x16x32_bf16 v[0:3], v[80:83], v[28:31], v[0:3]
	v_rcp_f32_e32 v28, v88
	v_rcp_f32_e32 v29, v89
	v_rcp_f32_e32 v30, v90
	v_rcp_f32_e32 v31, v91
	v_mfma_f32_16x16x32_bf16 v[4:7], v[76:79], v[92:95], v[4:7]
	v_mul_f32_e64 v78, v194, v28
	v_mul_f32_e64 v79, v195, v29
	v_pk_mul_f32 v[82:83], v[206:207], v[30:31]
	global_load_dwordx4 v[104:107], v[196:197], off
	global_load_dwordx4 v[108:111], v[196:197], off offset:1024
	global_load_dwordx4 v[112:115], v[196:197], off offset:2048
	global_load_dwordx4 v[116:119], v[196:197], off offset:3072
	global_load_dwordx4 v[120:123], v[198:199], off
	global_load_dwordx4 v[124:127], v[200:201], off
	global_load_dwordx4 v[128:131], v[202:203], off
	global_load_dwordx4 v[132:135], v[204:205], off
	s_nop 0
	v_mfma_f32_16x16x32_bf16 v[0:3], v[84:87], v[92:95], v[0:3]
	s_waitcnt vmcnt(0)
	v_lshlrev_b32_e32 v72, 16, v104
	v_and_b32_e32 v73, 0xffff0000, v104
	v_lshlrev_b32_e32 v28, 16, v105
	v_and_b32_e32 v29, 0xffff0000, v105
	v_lshlrev_b32_e32 v74, 16, v106
	v_and_b32_e32 v75, 0xffff0000, v106
	v_lshlrev_b32_e32 v76, 16, v107
	v_and_b32_e32 v77, 0xffff0000, v107
	v_pk_fma_f32 v[30:31], v[82:83], v[62:63], v[28:29] neg_lo:[1,0,0] neg_hi:[1,0,0]
	v_pk_fma_f32 v[28:29], v[82:83], v[54:55], v[76:77] neg_lo:[1,0,0] neg_hi:[1,0,0]
	v_pk_fma_f32 v[62:63], v[78:79], v[52:53], v[74:75] neg_lo:[1,0,0] neg_hi:[1,0,0]
	s_nop 0
	v_pk_fma_f32 v[72:73], v[78:79], v[60:61], v[72:73] neg_lo:[1,0,0] neg_hi:[1,0,0]
	v_pk_mul_f32 v[88:89], v[62:63], v[62:63]
	s_nop 0
	v_lshlrev_b32_e32 v60, 16, v108
	v_and_b32_e32 v61, 0xffff0000, v108
	v_lshlrev_b32_e32 v52, 16, v109
	v_and_b32_e32 v53, 0xffff0000, v109
	v_lshlrev_b32_e32 v74, 16, v110
	v_and_b32_e32 v75, 0xffff0000, v110
	v_lshlrev_b32_e32 v54, 16, v111
	v_and_b32_e32 v55, 0xffff0000, v111
	v_pk_fma_f32 v[46:47], v[82:83], v[46:47], v[52:53] neg_lo:[1,0,0] neg_hi:[1,0,0]
	v_pk_fma_f32 v[38:39], v[82:83], v[38:39], v[54:55] neg_lo:[1,0,0] neg_hi:[1,0,0]
	s_nop 0
	v_pk_fma_f32 v[76:77], v[78:79], v[44:45], v[60:61] neg_lo:[1,0,0] neg_hi:[1,0,0]
	v_pk_fma_f32 v[74:75], v[78:79], v[36:37], v[74:75] neg_lo:[1,0,0] neg_hi:[1,0,0]
	v_pk_fma_f32 v[88:89], v[72:73], v[72:73], v[88:89]
	s_nop 0
	v_lshlrev_b32_e32 v36, 16, v112
	v_and_b32_e32 v37, 0xffff0000, v112
	v_lshlrev_b32_e32 v44, 16, v113
	v_and_b32_e32 v45, 0xffff0000, v113
	v_lshlrev_b32_e32 v60, 16, v114
	v_and_b32_e32 v61, 0xffff0000, v114
	v_lshlrev_b32_e32 v54, 16, v115
	v_and_b32_e32 v55, 0xffff0000, v115
	v_pk_fma_f32 v[52:53], v[82:83], v[66:67], v[44:45] neg_lo:[1,0,0] neg_hi:[1,0,0]
	v_pk_fma_f32 v[66:67], v[78:79], v[64:65], v[36:37] neg_lo:[1,0,0] neg_hi:[1,0,0]
	v_pk_fma_f32 v[44:45], v[82:83], v[26:27], v[54:55] neg_lo:[1,0,0] neg_hi:[1,0,0]
	v_pk_fma_f32 v[64:65], v[78:79], v[24:25], v[60:61] neg_lo:[1,0,0] neg_hi:[1,0,0]
	s_nop 0
	v_mov_b32_e32 v90, v65
	v_mov_b32_e32 v91, v67
	v_pk_mul_f32 v[90:91], v[90:91], v[90:91]
	s_nop 0
	v_lshlrev_b32_e32 v36, 16, v116
	v_and_b32_e32 v37, 0xffff0000, v116
	v_lshlrev_b32_e32 v84, 16, v118
	v_and_b32_e32 v85, 0xffff0000, v118
	v_lshlrev_b32_e32 v26, 16, v119
	v_and_b32_e32 v27, 0xffff0000, v119
	v_pk_fma_f32 v[80:81], v[78:79], v[12:13], v[36:37] neg_lo:[1,0,0] neg_hi:[1,0,0]
	v_pk_fma_f32 v[54:55], v[82:83], v[6:7], v[26:27] neg_lo:[1,0,0] neg_hi:[1,0,0]
	v_pk_fma_f32 v[78:79], v[78:79], v[4:5], v[84:85] neg_lo:[1,0,0] neg_hi:[1,0,0]
	v_rcp_f32_e32 v4, v68
	v_rcp_f32_e32 v5, v69
	v_rcp_f32_e32 v6, v70
	v_rcp_f32_e32 v7, v71
	v_lshlrev_b32_e32 v24, 16, v117
	v_pk_mul_f32 v[68:69], v[194:195], v[4:5]
	v_and_b32_e32 v25, 0xffff0000, v117
	v_pk_mul_f32 v[70:71], v[206:207], v[6:7]
	s_nop 0
	v_pk_fma_f32 v[60:61], v[82:83], v[14:15], v[24:25] neg_lo:[1,0,0] neg_hi:[1,0,0]
	v_mov_b32_e32 v92, v79
	v_mov_b32_e32 v93, v81
	v_pk_mul_f32 v[92:93], v[92:93], v[92:93]
	s_nop 0
	v_lshlrev_b32_e32 v12, 16, v120
	v_and_b32_e32 v13, 0xffff0000, v120
	v_lshlrev_b32_e32 v4, 16, v121
	v_and_b32_e32 v5, 0xffff0000, v121
	v_lshlrev_b32_e32 v14, 16, v122
	v_and_b32_e32 v15, 0xffff0000, v122
	v_lshlrev_b32_e32 v24, 16, v123
	v_and_b32_e32 v25, 0xffff0000, v123
	v_pk_fma_f32 v[6:7], v[70:71], v[58:59], v[4:5] neg_lo:[1,0,0] neg_hi:[1,0,0]
	v_pk_fma_f32 v[26:27], v[68:69], v[56:57], v[12:13] neg_lo:[1,0,0] neg_hi:[1,0,0]
	v_pk_fma_f32 v[4:5], v[70:71], v[50:51], v[24:25] neg_lo:[1,0,0] neg_hi:[1,0,0]
	v_pk_fma_f32 v[24:25], v[68:69], v[48:49], v[14:15] neg_lo:[1,0,0] neg_hi:[1,0,0]
	s_nop 0
	s_nop 0
	v_lshlrev_b32_e32 v36, 16, v124
	v_and_b32_e32 v37, 0xffff0000, v124
	v_lshlrev_b32_e32 v12, 16, v125
	v_and_b32_e32 v13, 0xffff0000, v125
	v_lshlrev_b32_e32 v48, 16, v126
	v_and_b32_e32 v49, 0xffff0000, v126
	v_lshlrev_b32_e32 v50, 16, v127
	v_and_b32_e32 v51, 0xffff0000, v127
	v_pk_fma_f32 v[14:15], v[70:71], v[42:43], v[12:13] neg_lo:[1,0,0] neg_hi:[1,0,0]
	v_pk_fma_f32 v[36:37], v[68:69], v[40:41], v[36:37] neg_lo:[1,0,0] neg_hi:[1,0,0]
	s_nop 0
	v_pk_fma_f32 v[12:13], v[70:71], v[34:35], v[50:51] neg_lo:[1,0,0] neg_hi:[1,0,0]
	v_pk_fma_f32 v[32:33], v[68:69], v[32:33], v[48:49] neg_lo:[1,0,0] neg_hi:[1,0,0]
	s_nop 0
	v_lshlrev_b32_e32 v34, 16, v128
	v_and_b32_e32 v35, 0xffff0000, v128
	v_lshlrev_b32_e32 v40, 16, v129
	v_and_b32_e32 v41, 0xffff0000, v129
	v_lshlrev_b32_e32 v48, 16, v130
	v_and_b32_e32 v49, 0xffff0000, v130
	v_lshlrev_b32_e32 v42, 16, v131
	v_and_b32_e32 v43, 0xffff0000, v131
	v_pk_fma_f32 v[18:19], v[70:71], v[18:19], v[40:41] neg_lo:[1,0,0] neg_hi:[1,0,0]
	v_pk_fma_f32 v[34:35], v[68:69], v[16:17], v[34:35] neg_lo:[1,0,0] neg_hi:[1,0,0]
	v_pk_fma_f32 v[16:17], v[70:71], v[22:23], v[42:43] neg_lo:[1,0,0] neg_hi:[1,0,0]
	s_nop 0
; DEV bf16_t f2bf(float f) { unsigned u = __float_as_uint(f); u += 0x7fffu + ((u >> 16) & 1u); return (bf16_t)(u >> 16); }
; DEV int lv(int x) { asm volatile("" : "+v"(x)); return x; }
; DEV void attn_store16(f32x4 (&o)[2][8], const float* __restrict__ gain, float oscale, bf16_t* __restrict__ mix, int q0, int colbase) {
;   const int tid = lv(threadIdx.x), wid = tid >> 6, lane = tid & 63, fr = lane & 15, fq = lane >> 4;
;   unsigned char* sc = shm_raw + wid * 8704;
;   float gn[8];
; #pragma unroll
;   for (int cb = 0; cb < 8; ++cb) gn[cb] = gain[16 * cb + fr] * oscale;
; #pragma unroll
;   for (int g = 0; g < 2; ++g)
; #pragma unroll
;     for (int j = 0; j < 4; ++j) {
;       float ss = 0.f;
; #pragma unroll
;       for (int cb = 0; cb < 8; ++cb) ss += o[g][cb][j] * o[g][cb][j];
;       ss += __shfl_xor(ss, 1); ss += __shfl_xor(ss, 2); ss += __shfl_xor(ss, 4); ss += __shfl_xor(ss, 8);
;       const float rn = rsqrtf(ss * (1.f / 128.f) + EPS);
;       const int sl = 16 * g + 4 * fq + j;
; #pragma unroll
;       for (int cb = 0; cb < 8; ++cb) *reinterpret_cast<bf16_t*>(sc + sl * 272 + (16 * cb + fr) * 2) = f2bf(o[g][cb][j] * rn * gn[cb]);
	v_pk_fma_f32 v[20:21], v[68:69], v[20:21], v[48:49] neg_lo:[1,0,0] neg_hi:[1,0,0]
	s_nop 0
	v_lshlrev_b32_e32 v22, 16, v132
	v_and_b32_e32 v23, 0xffff0000, v132
	v_lshlrev_b32_e32 v48, 16, v134
	v_and_b32_e32 v49, 0xffff0000, v134
	v_lshlrev_b32_e32 v42, 16, v135
	v_and_b32_e32 v43, 0xffff0000, v135
	v_pk_fma_f32 v[8:9], v[68:69], v[8:9], v[22:23] neg_lo:[1,0,0] neg_hi:[1,0,0]
	v_mov_b32_e32 v22, v210
	v_pk_fma_f32 v[2:3], v[70:71], v[2:3], v[42:43] neg_lo:[1,0,0] neg_hi:[1,0,0]
	v_lshlrev_b32_e32 v40, 16, v133
	v_ashrrev_i32_e32 v43, 6, v22
	v_and_b32_e32 v41, 0xffff0000, v133
	v_pk_fma_f32 v[0:1], v[68:69], v[0:1], v[48:49] neg_lo:[1,0,0] neg_hi:[1,0,0]
	v_and_b32_e32 v48, 15, v22
	v_mul_lo_u32 v23, v43, s0
	v_readlane_b32 s0, v255, 61
	v_pk_fma_f32 v[10:11], v[70:71], v[10:11], v[40:41] neg_lo:[1,0,0] neg_hi:[1,0,0]
	v_lshlrev_b32_e32 v40, 2, v48
	v_readlane_b32 s1, v255, 62
	v_bfe_u32 v42, v22, 4, 2
	v_add_u32_e32 v57, 0, v23
	v_lshlrev_b32_e32 v70, 1, v48
	v_mov_b32_e32 v22, v74
	v_mov_b32_e32 v23, v76
	global_load_dword v96, v40, s[0:1]
	global_load_dword v97, v40, s[0:1] offset:64
	global_load_dword v98, v40, s[0:1] offset:128
	global_load_dword v99, v40, s[0:1] offset:192
	global_load_dword v100, v40, s[0:1] offset:256
	global_load_dword v101, v40, s[0:1] offset:320
	global_load_dword v102, v40, s[0:1] offset:384
	global_load_dword v103, v40, s[0:1] offset:448
	s_nop 0
	v_pk_mul_f32 v[22:23], v[22:23], v[22:23]
	v_lshlrev_b32_e32 v192, 4, v48
	v_mov_b32_e32 v95, v22
	s_waitcnt vmcnt(0)
	v_mul_f32_e32 v49, v222, v96
	s_nop 0
	s_nop 0
	v_mul_f32_e32 v50, v222, v97
	s_nop 0
	s_nop 0
	v_mul_f32_e32 v51, v222, v98
	s_nop 0
	s_nop 0
	v_mul_f32_e32 v56, v222, v99
	s_nop 0
	s_nop 0
	v_mul_f32_e32 v58, v222, v100
	s_nop 0
	s_nop 0
	v_mul_f32_e32 v59, v222, v101
	s_nop 0
	s_nop 0
	v_mul_f32_e32 v68, v222, v102
	s_nop 0
	v_mov_b32_e32 v41, v66
	s_mov_b32 s0, 0x358637bd
	s_nop 0
	v_mul_f32_e32 v69, v222, v103
	v_mov_b32_e32 v40, v64
	v_pk_mul_f32 v[82:83], v[40:41], v[40:41]
	v_mov_b32_e32 v40, v78
	v_mov_b32_e32 v41, v80
	v_pk_mul_f32 v[84:85], v[40:41], v[40:41]
	v_mul_u32_u24_e32 v40, 0x440, v42
	v_add3_u32 v70, v57, v70, v40
	v_mov_b32_e32 v40, v75
	v_mov_b32_e32 v41, v77
	v_pk_mul_f32 v[86:87], v[40:41], v[40:41]
	v_pk_mul_f32 v[40:41], v[28:29], v[28:29]
	v_mov_b32_e32 v22, v87
	v_mov_b32_e32 v94, v86
	v_pk_add_f32 v[22:23], v[88:89], v[22:23] op_sel:[1,0] op_sel_hi:[0,1]
	v_pk_add_f32 v[22:23], v[94:95], v[22:23]
	v_mov_b32_e32 v86, v91
	v_mov_b32_e32 v87, v83
	v_pk_add_f32 v[22:23], v[86:87], v[22:23]
	v_mov_b32_e32 v91, v82
	v_pk_add_f32 v[22:23], v[90:91], v[22:23]
	v_mov_b32_e32 v82, v93
	v_mov_b32_e32 v83, v85
	v_pk_add_f32 v[22:23], v[82:83], v[22:23]
	v_mov_b32_e32 v93, v84
	v_pk_add_f32 v[22:23], v[92:93], v[22:23]
	ds_bpermute_b32 v83, v221, v23
	ds_bpermute_b32 v82, v221, v22
	v_pk_fma_f32 v[40:41], v[30:31], v[30:31], v[40:41]
	s_waitcnt lgkmcnt(0)
	v_pk_add_f32 v[22:23], v[22:23], v[82:83]
	ds_bpermute_b32 v83, v220, v23
	ds_bpermute_b32 v82, v220, v22
	s_waitcnt lgkmcnt(0)
	v_pk_add_f32 v[22:23], v[22:23], v[82:83]
	ds_bpermute_b32 v83, v219, v23
	ds_bpermute_b32 v82, v219, v22
	s_waitcnt lgkmcnt(0)
	v_pk_add_f32 v[22:23], v[22:23], v[82:83]
	ds_bpermute_b32 v83, v218, v23
	ds_bpermute_b32 v82, v218, v22
	s_waitcnt lgkmcnt(0)
	v_pk_add_f32 v[82:83], v[22:23], v[82:83]
	v_mov_b64_e32 v[22:23], s[0:1]
	v_pk_fma_f32 v[82:83], v[82:83], s[4:5], v[22:23] op_sel_hi:[1,0,0]
	s_nop 0
	v_mul_f32_e32 v71, 0x4b800000, v83
	v_cmp_gt_f32_e64 s[0:1], s33, v83
	v_cmp_gt_f32_e32 vcc, s33, v82
	s_nop 0
	v_cndmask_b32_e64 v71, v83, v71, s[0:1]
	v_rsq_f32_e32 v71, v71
	s_nop 0
	v_mul_f32_e32 v83, 0x45800000, v71
	v_cndmask_b32_e64 v71, v71, v83, s[0:1]
	v_mul_f32_e32 v72, v72, v71
	v_mul_f32_e32 v72, v49, v72
	v_bfe_u32 v83, v72, 16, 1
	v_mul_f32_e32 v62, v62, v71
	v_add3_u32 v72, v72, v83, s2
	v_mul_f32_e32 v62, v50, v62
	ds_write_b16_d16_hi v70, v72
	v_bfe_u32 v72, v62, 16, 1
	v_add3_u32 v62, v62, v72, s2
	ds_write_b16_d16_hi v70, v62 offset:32
	v_mul_f32_e32 v62, v76, v71
	v_mul_f32_e32 v62, v51, v62
	v_bfe_u32 v72, v62, 16, 1
	v_add3_u32 v62, v62, v72, s2
	ds_write_b16_d16_hi v70, v62 offset:64
	v_mul_f32_e32 v62, v74, v71
	v_mul_f32_e32 v62, v56, v62
	v_bfe_u32 v72, v62, 16, 1
	v_add3_u32 v62, v62, v72, s2
	ds_write_b16_d16_hi v70, v62 offset:96
	v_mul_f32_e32 v62, v66, v71
	v_mul_f32_e32 v62, v58, v62
	v_bfe_u32 v66, v62, 16, 1
	v_add3_u32 v62, v62, v66, s2
	ds_write_b16_d16_hi v70, v62 offset:128
	v_mul_f32_e32 v62, v64, v71
	v_mul_f32_e32 v62, v59, v62
	v_bfe_u32 v64, v62, 16, 1
	v_add3_u32 v62, v62, v64, s2
	ds_write_b16_d16_hi v70, v62 offset:160
	v_mul_f32_e32 v62, v80, v71
	v_mul_f32_e32 v62, v68, v62
	v_bfe_u32 v64, v62, 16, 1
	v_add3_u32 v62, v62, v64, s2
	ds_write_b16_d16_hi v70, v62 offset:192
	v_mul_f32_e32 v62, v78, v71
	v_mul_f32_e32 v62, v69, v62
	v_bfe_u32 v64, v62, 16, 1
	v_add3_u32 v62, v62, v64, s2
	ds_write_b16_d16_hi v70, v62 offset:224
	v_mul_f32_e32 v62, 0x4b800000, v82
	v_cndmask_b32_e32 v62, v82, v62, vcc
	v_rsq_f32_e32 v62, v62
	v_mov_b32_e32 v72, v39
	v_mov_b32_e32 v74, v45
	v_mov_b32_e32 v76, v55
	v_mul_f32_e32 v64, 0x45800000, v62
	v_cndmask_b32_e32 v62, v62, v64, vcc
	v_mul_f32_e32 v64, v73, v62
	v_mul_f32_e32 v64, v49, v64
	v_bfe_u32 v66, v64, 16, 1
	v_mul_f32_e32 v63, v63, v62
	v_add3_u32 v64, v64, v66, s2
	v_mul_f32_e32 v63, v50, v63
	ds_write_b16_d16_hi v70, v64 offset:272
	v_bfe_u32 v64, v63, 16, 1
	v_add3_u32 v63, v63, v64, s2
	ds_write_b16_d16_hi v70, v63 offset:304
	v_mul_f32_e32 v63, v77, v62
	v_mul_f32_e32 v63, v51, v63
	v_bfe_u32 v64, v63, 16, 1
	v_add3_u32 v63, v63, v64, s2
; DEV bf16_t f2bf(float f) { unsigned u = __float_as_uint(f); u += 0x7fffu + ((u >> 16) & 1u); return (bf16_t)(u >> 16); }
; DEV void attn_store16(f32x4 (&o)[2][8], const float* __restrict__ gain, float oscale, bf16_t* __restrict__ mix, int q0, int colbase) {
;     ...
;   for (int g = 0; g < 2; ++g)
; #pragma unroll
;     for (int j = 0; j < 4; ++j) {
;       float ss = 0.f;
; #pragma unroll
;       for (int cb = 0; cb < 8; ++cb) ss += o[g][cb][j] * o[g][cb][j];
;       ss += __shfl_xor(ss, 1); ss += __shfl_xor(ss, 2); ss += __shfl_xor(ss, 4); ss += __shfl_xor(ss, 8);
;       const float rn = rsqrtf(ss * (1.f / 128.f) + EPS);
;       const int sl = 16 * g + 4 * fq + j;
; #pragma unroll
;       for (int cb = 0; cb < 8; ++cb) *reinterpret_cast<bf16_t*>(sc + sl * 272 + (16 * cb + fr) * 2) = f2bf(o[g][cb][j] * rn * gn[cb]);
	ds_write_b16_d16_hi v70, v63 offset:336
	v_mul_f32_e32 v63, v75, v62
	v_mul_f32_e32 v63, v56, v63
	v_bfe_u32 v64, v63, 16, 1
	v_add3_u32 v63, v63, v64, s2
	ds_write_b16_d16_hi v70, v63 offset:368
	v_mul_f32_e32 v63, v67, v62
	v_mul_f32_e32 v63, v58, v63
	v_bfe_u32 v64, v63, 16, 1
	v_add3_u32 v63, v63, v64, s2
	ds_write_b16_d16_hi v70, v63 offset:400
	v_mul_f32_e32 v63, v65, v62
	v_mul_f32_e32 v63, v59, v63
	v_bfe_u32 v64, v63, 16, 1
	v_add3_u32 v63, v63, v64, s2
	ds_write_b16_d16_hi v70, v63 offset:432
	v_mul_f32_e32 v63, v81, v62
	v_mul_f32_e32 v63, v68, v63
	v_bfe_u32 v64, v63, 16, 1
	v_mul_f32_e32 v62, v79, v62
	v_add3_u32 v63, v63, v64, s2
	v_mul_f32_e32 v62, v69, v62
	ds_write_b16_d16_hi v70, v63 offset:464
	v_bfe_u32 v63, v62, 16, 1
	v_add3_u32 v62, v62, v63, s2
	ds_write_b16_d16_hi v70, v62 offset:496
	v_mov_b32_e32 v62, v38
	v_mov_b32_e32 v63, v46
	v_mov_b32_e32 v73, v47
	v_pk_mul_f32 v[62:63], v[62:63], v[62:63]
	v_pk_mul_f32 v[72:73], v[72:73], v[72:73]
	v_mov_b32_e32 v64, v44
	v_mov_b32_e32 v65, v52
	v_mov_b32_e32 v75, v53
	v_mov_b32_e32 v79, v62
	v_mov_b32_e32 v62, v73
	v_pk_mul_f32 v[64:65], v[64:65], v[64:65]
	v_pk_mul_f32 v[74:75], v[74:75], v[74:75]
	v_mov_b32_e32 v78, v72
	v_pk_add_f32 v[40:41], v[40:41], v[62:63] op_sel:[1,0] op_sel_hi:[0,1]
	v_mov_b32_e32 v66, v54
	v_mov_b32_e32 v67, v60
	v_mov_b32_e32 v77, v61
	v_pk_add_f32 v[40:41], v[78:79], v[40:41]
	v_mov_b32_e32 v62, v75
	v_mov_b32_e32 v63, v65
	v_pk_mul_f32 v[66:67], v[66:67], v[66:67]
	v_pk_mul_f32 v[76:77], v[76:77], v[76:77]
	v_pk_add_f32 v[40:41], v[62:63], v[40:41]
	v_mov_b32_e32 v75, v64
	v_pk_add_f32 v[40:41], v[74:75], v[40:41]
	v_mov_b32_e32 v62, v77
	v_mov_b32_e32 v63, v67
	v_pk_add_f32 v[40:41], v[62:63], v[40:41]
	v_mov_b32_e32 v77, v66
	v_pk_add_f32 v[40:41], v[76:77], v[40:41]
	ds_bpermute_b32 v63, v221, v41
	ds_bpermute_b32 v62, v221, v40
	s_waitcnt lgkmcnt(0)
	v_pk_add_f32 v[40:41], v[40:41], v[62:63]
	ds_bpermute_b32 v63, v220, v41
	ds_bpermute_b32 v62, v220, v40
	s_waitcnt lgkmcnt(0)
	v_pk_add_f32 v[40:41], v[40:41], v[62:63]
	ds_bpermute_b32 v63, v219, v41
	ds_bpermute_b32 v62, v219, v40
	s_waitcnt lgkmcnt(0)
	v_pk_add_f32 v[40:41], v[40:41], v[62:63]
	ds_bpermute_b32 v63, v218, v41
	ds_bpermute_b32 v62, v218, v40
	s_waitcnt lgkmcnt(0)
	v_pk_add_f32 v[40:41], v[40:41], v[62:63]
	s_nop 0
	v_pk_fma_f32 v[40:41], v[40:41], s[4:5], v[22:23] op_sel_hi:[1,0,0]
	s_nop 0
	v_mul_f32_e32 v62, 0x4b800000, v41
	v_cmp_gt_f32_e64 s[0:1], s33, v41
	v_cmp_gt_f32_e32 vcc, s33, v40
	s_nop 0
	v_cndmask_b32_e64 v41, v41, v62, s[0:1]
	v_rsq_f32_e32 v41, v41
	s_nop 0
	v_mul_f32_e32 v62, 0x45800000, v41
	v_cndmask_b32_e64 v41, v41, v62, s[0:1]
	v_mul_f32_e32 v30, v30, v41
	v_mul_f32_e32 v30, v49, v30
	v_bfe_u32 v62, v30, 16, 1
	v_mul_f32_e32 v28, v28, v41
	v_add3_u32 v30, v30, v62, s2
	v_mul_f32_e32 v28, v50, v28
	ds_write_b16_d16_hi v70, v30 offset:544
	v_bfe_u32 v30, v28, 16, 1
	v_add3_u32 v28, v28, v30, s2
	ds_write_b16_d16_hi v70, v28 offset:576
	v_mul_f32_e32 v28, v46, v41
	v_mul_f32_e32 v28, v51, v28
	v_bfe_u32 v30, v28, 16, 1
	v_add3_u32 v28, v28, v30, s2
	ds_write_b16_d16_hi v70, v28 offset:608
	v_mul_f32_e32 v28, v38, v41
	v_mul_f32_e32 v28, v56, v28
	v_bfe_u32 v30, v28, 16, 1
	v_add3_u32 v28, v28, v30, s2
	ds_write_b16_d16_hi v70, v28 offset:640
	v_mul_f32_e32 v28, v52, v41
	v_mul_f32_e32 v28, v58, v28
	v_bfe_u32 v30, v28, 16, 1
	v_add3_u32 v28, v28, v30, s2
	ds_write_b16_d16_hi v70, v28 offset:672
	v_mul_f32_e32 v28, v44, v41
	v_mul_f32_e32 v28, v59, v28
	v_bfe_u32 v30, v28, 16, 1
	v_add3_u32 v28, v28, v30, s2
	ds_write_b16_d16_hi v70, v28 offset:704
	v_mul_f32_e32 v28, v60, v41
	v_mul_f32_e32 v28, v68, v28
	v_bfe_u32 v30, v28, 16, 1
	v_add3_u32 v28, v28, v30, s2
	ds_write_b16_d16_hi v70, v28 offset:736
	v_mul_f32_e32 v28, v54, v41
	v_mul_f32_e32 v28, v69, v28
	v_bfe_u32 v30, v28, 16, 1
	v_add3_u32 v28, v28, v30, s2
	ds_write_b16_d16_hi v70, v28 offset:768
	v_mul_f32_e32 v28, 0x4b800000, v40
	v_cndmask_b32_e32 v28, v40, v28, vcc
	v_rsq_f32_e32 v28, v28
	v_mov_b32_e32 v52, v21
	v_mov_b32_e32 v54, v1
	v_mul_f32_e32 v30, 0x45800000, v28
	v_cndmask_b32_e32 v28, v28, v30, vcc
	v_mul_f32_e32 v30, v31, v28
	v_mul_f32_e32 v30, v49, v30
	v_bfe_u32 v31, v30, 16, 1
	v_mul_f32_e32 v29, v29, v28
	v_add3_u32 v30, v30, v31, s2
	v_mul_f32_e32 v29, v50, v29
	ds_write_b16_d16_hi v70, v30 offset:816
	v_bfe_u32 v30, v29, 16, 1
	v_add3_u32 v29, v29, v30, s2
	ds_write_b16_d16_hi v70, v29 offset:848
	v_mul_f32_e32 v29, v47, v28
	v_mul_f32_e32 v29, v51, v29
	v_bfe_u32 v30, v29, 16, 1
	v_add3_u32 v29, v29, v30, s2
	ds_write_b16_d16_hi v70, v29 offset:880
	v_mul_f32_e32 v29, v39, v28
	v_mul_f32_e32 v29, v56, v29
	v_bfe_u32 v30, v29, 16, 1
	v_add3_u32 v29, v29, v30, s2
	ds_write_b16_d16_hi v70, v29 offset:912
	v_mul_f32_e32 v29, v53, v28
	v_mul_f32_e32 v29, v58, v29
	v_bfe_u32 v30, v29, 16, 1
	v_add3_u32 v29, v29, v30, s2
	ds_write_b16_d16_hi v70, v29 offset:944
	v_mul_f32_e32 v29, v45, v28
	v_mul_f32_e32 v29, v59, v29
	v_bfe_u32 v30, v29, 16, 1
	v_add3_u32 v29, v29, v30, s2
	ds_write_b16_d16_hi v70, v29 offset:976
	v_mul_f32_e32 v29, v61, v28
	v_mul_f32_e32 v29, v68, v29
	v_bfe_u32 v30, v29, 16, 1
	v_mul_f32_e32 v28, v55, v28
	v_add3_u32 v29, v29, v30, s2
	v_mul_f32_e32 v28, v69, v28
	ds_write_b16_d16_hi v70, v29 offset:1008
	v_bfe_u32 v29, v28, 16, 1
	v_add3_u32 v28, v28, v29, s2
	ds_write_b16_d16_hi v70, v28 offset:1040
	v_mov_b32_e32 v28, v32
	v_mov_b32_e32 v29, v36
	v_pk_mul_f32 v[30:31], v[28:29], v[28:29]
	v_mov_b32_e32 v28, v20
	v_mov_b32_e32 v29, v34
	v_pk_mul_f32 v[38:39], v[28:29], v[28:29]
	v_mov_b32_e32 v28, v0
	v_mov_b32_e32 v29, v8
	v_pk_mul_f32 v[40:41], v[28:29], v[28:29]
	v_mov_b32_e32 v28, v33
	v_mov_b32_e32 v29, v37
	v_pk_mul_f32 v[44:45], v[28:29], v[28:29]
	v_pk_mul_f32 v[46:47], v[24:25], v[24:25]
	v_mov_b32_e32 v53, v35
	v_pk_fma_f32 v[46:47], v[26:27], v[26:27], v[46:47]
	v_mov_b32_e32 v61, v30
	v_mov_b32_e32 v30, v45
	v_pk_mul_f32 v[52:53], v[52:53], v[52:53]
	v_mov_b32_e32 v60, v44
	v_pk_add_f32 v[30:31], v[46:47], v[30:31] op_sel:[1,0] op_sel_hi:[0,1]
	v_mov_b32_e32 v55, v9
	v_pk_add_f32 v[30:31], v[60:61], v[30:31]
	v_mov_b32_e32 v44, v53
	v_mov_b32_e32 v45, v39
	v_pk_mul_f32 v[54:55], v[54:55], v[54:55]
	v_pk_add_f32 v[30:31], v[44:45], v[30:31]
	v_mov_b32_e32 v53, v38
	v_pk_add_f32 v[30:31], v[52:53], v[30:31]
	v_mov_b32_e32 v38, v55
	v_mov_b32_e32 v39, v41
	v_pk_add_f32 v[30:31], v[38:39], v[30:31]
	v_mov_b32_e32 v55, v40
	v_pk_add_f32 v[30:31], v[54:55], v[30:31]
	ds_bpermute_b32 v39, v221, v31
	ds_bpermute_b32 v38, v221, v30
	v_pk_mul_f32 v[28:29], v[4:5], v[4:5]
	s_waitcnt lgkmcnt(0)
; DEV bf16_t f2bf(float f) { unsigned u = __float_as_uint(f); u += 0x7fffu + ((u >> 16) & 1u); return (bf16_t)(u >> 16); }
; DEV void attn_store16(f32x4 (&o)[2][8], const float* __restrict__ gain, float oscale, bf16_t* __restrict__ mix, int q0, int colbase) {
;     ...
;   for (int g = 0; g < 2; ++g)
; #pragma unroll
;     for (int j = 0; j < 4; ++j) {
;       float ss = 0.f;
; #pragma unroll
;       for (int cb = 0; cb < 8; ++cb) ss += o[g][cb][j] * o[g][cb][j];
;       ss += __shfl_xor(ss, 1); ss += __shfl_xor(ss, 2); ss += __shfl_xor(ss, 4); ss += __shfl_xor(ss, 8);
;       const float rn = rsqrtf(ss * (1.f / 128.f) + EPS);
;       const int sl = 16 * g + 4 * fq + j;
; #pragma unroll
;       for (int cb = 0; cb < 8; ++cb) *reinterpret_cast<bf16_t*>(sc + sl * 272 + (16 * cb + fr) * 2) = f2bf(o[g][cb][j] * rn * gn[cb]);
	v_pk_add_f32 v[30:31], v[30:31], v[38:39]
	ds_bpermute_b32 v39, v220, v31
	ds_bpermute_b32 v38, v220, v30
	v_pk_fma_f32 v[28:29], v[6:7], v[6:7], v[28:29]
	s_waitcnt lgkmcnt(0)
	v_pk_add_f32 v[30:31], v[30:31], v[38:39]
	ds_bpermute_b32 v39, v219, v31
	ds_bpermute_b32 v38, v219, v30
	s_waitcnt lgkmcnt(0)
	v_pk_add_f32 v[30:31], v[30:31], v[38:39]
	ds_bpermute_b32 v39, v218, v31
	ds_bpermute_b32 v38, v218, v30
	s_waitcnt lgkmcnt(0)
	v_pk_add_f32 v[30:31], v[30:31], v[38:39]
	s_nop 0
	v_pk_fma_f32 v[30:31], v[30:31], s[4:5], v[22:23] op_sel_hi:[1,0,0]
	s_nop 0
	v_mul_f32_e32 v38, 0x4b800000, v31
	v_cmp_gt_f32_e64 s[0:1], s33, v31
	v_cmp_gt_f32_e32 vcc, s33, v30
	s_nop 0
	v_cndmask_b32_e64 v31, v31, v38, s[0:1]
	v_rsq_f32_e32 v31, v31
	s_nop 0
	v_mul_f32_e32 v38, 0x45800000, v31
	v_cndmask_b32_e64 v31, v31, v38, s[0:1]
	v_mul_f32_e32 v26, v26, v31
	v_mul_f32_e32 v26, v49, v26
	v_bfe_u32 v38, v26, 16, 1
	v_mul_f32_e32 v24, v24, v31
	v_add3_u32 v26, v26, v38, s2
	v_mul_f32_e32 v24, v50, v24
	ds_write_b16_d16_hi v70, v26 offset:4352
	v_bfe_u32 v26, v24, 16, 1
	v_add3_u32 v24, v24, v26, s2
	ds_write_b16_d16_hi v70, v24 offset:4384
	v_mul_f32_e32 v24, v36, v31
	v_mul_f32_e32 v24, v51, v24
	v_bfe_u32 v26, v24, 16, 1
	v_add3_u32 v24, v24, v26, s2
	ds_write_b16_d16_hi v70, v24 offset:4416
	v_mul_f32_e32 v24, v32, v31
	v_mul_f32_e32 v24, v56, v24
	v_bfe_u32 v26, v24, 16, 1
	v_add3_u32 v24, v24, v26, s2
	ds_write_b16_d16_hi v70, v24 offset:4448
	v_mul_f32_e32 v24, v34, v31
	v_mul_f32_e32 v24, v58, v24
	v_bfe_u32 v26, v24, 16, 1
	v_mul_f32_e32 v20, v20, v31
	v_add3_u32 v24, v24, v26, s2
	v_mul_f32_e32 v20, v59, v20
	ds_write_b16_d16_hi v70, v24 offset:4480
	v_bfe_u32 v24, v20, 16, 1
	v_mul_f32_e32 v8, v8, v31
	v_add3_u32 v20, v20, v24, s2
	v_mul_f32_e32 v8, v68, v8
	ds_write_b16_d16_hi v70, v20 offset:4512
	v_bfe_u32 v20, v8, 16, 1
	v_mul_f32_e32 v0, v0, v31
	v_add3_u32 v8, v8, v20, s2
	v_mul_f32_e32 v0, v69, v0
	ds_write_b16_d16_hi v70, v8 offset:4544
	v_bfe_u32 v8, v0, 16, 1
	v_add3_u32 v0, v0, v8, s2
	ds_write_b16_d16_hi v70, v0 offset:4576
	v_mul_f32_e32 v0, 0x4b800000, v30
	v_cndmask_b32_e32 v0, v30, v0, vcc
	v_rsq_f32_e32 v0, v0
	v_mov_b32_e32 v24, v13
	v_mov_b32_e32 v26, v17
	v_mov_b32_e32 v30, v3
	v_mul_f32_e32 v8, 0x45800000, v0
	v_cndmask_b32_e32 v0, v0, v8, vcc
	v_mul_f32_e32 v8, v27, v0
	v_mul_f32_e32 v8, v49, v8
	v_bfe_u32 v20, v8, 16, 1
	v_add3_u32 v8, v8, v20, s2
	ds_write_b16_d16_hi v70, v8 offset:4624
	v_mul_f32_e32 v8, v25, v0
	v_mul_f32_e32 v8, v50, v8
	v_bfe_u32 v20, v8, 16, 1
	v_add3_u32 v8, v8, v20, s2
	ds_write_b16_d16_hi v70, v8 offset:4656
	v_mul_f32_e32 v8, v37, v0
	v_mul_f32_e32 v8, v51, v8
	v_bfe_u32 v20, v8, 16, 1
	v_add3_u32 v8, v8, v20, s2
	ds_write_b16_d16_hi v70, v8 offset:4688
	v_mul_f32_e32 v8, v33, v0
	v_mul_f32_e32 v8, v56, v8
	v_bfe_u32 v20, v8, 16, 1
	v_add3_u32 v8, v8, v20, s2
	ds_write_b16_d16_hi v70, v8 offset:4720
	v_mul_f32_e32 v8, v35, v0
	v_mul_f32_e32 v8, v58, v8
	v_bfe_u32 v20, v8, 16, 1
	v_add3_u32 v8, v8, v20, s2
	ds_write_b16_d16_hi v70, v8 offset:4752
	v_mul_f32_e32 v8, v21, v0
	v_mul_f32_e32 v8, v59, v8
	v_bfe_u32 v20, v8, 16, 1
	v_add3_u32 v8, v8, v20, s2
	ds_write_b16_d16_hi v70, v8 offset:4784
	v_mul_f32_e32 v8, v9, v0
	v_mul_f32_e32 v0, v1, v0
	v_mul_f32_e32 v0, v69, v0
	v_bfe_u32 v1, v0, 16, 1
	v_mul_f32_e32 v8, v68, v8
	v_add3_u32 v0, v0, v1, s2
	v_bfe_u32 v9, v8, 16, 1
	ds_write_b16_d16_hi v70, v0 offset:4848
	v_mov_b32_e32 v0, v12
	v_mov_b32_e32 v1, v14
	v_mov_b32_e32 v25, v15
	v_add3_u32 v8, v8, v9, s2
	v_pk_mul_f32 v[0:1], v[0:1], v[0:1]
	v_pk_mul_f32 v[24:25], v[24:25], v[24:25]
	ds_write_b16_d16_hi v70, v8 offset:4816
	v_mov_b32_e32 v8, v16
	v_mov_b32_e32 v9, v18
	v_mov_b32_e32 v27, v19
	v_mov_b32_e32 v33, v0
	v_mov_b32_e32 v0, v25
	v_pk_mul_f32 v[8:9], v[8:9], v[8:9]
	v_pk_mul_f32 v[26:27], v[26:27], v[26:27]
	v_mov_b32_e32 v32, v24
	v_pk_add_f32 v[0:1], v[28:29], v[0:1] op_sel:[1,0] op_sel_hi:[0,1]
	v_mov_b32_e32 v20, v2
	v_mov_b32_e32 v21, v10
	v_mov_b32_e32 v31, v11
	v_pk_add_f32 v[0:1], v[32:33], v[0:1]
	v_mov_b32_e32 v24, v27
	v_mov_b32_e32 v25, v9
	v_pk_mul_f32 v[20:21], v[20:21], v[20:21]
	v_pk_mul_f32 v[30:31], v[30:31], v[30:31]
	v_pk_add_f32 v[0:1], v[24:25], v[0:1]
	v_mov_b32_e32 v27, v8
	v_pk_add_f32 v[0:1], v[26:27], v[0:1]
	v_mov_b32_e32 v8, v31
	v_mov_b32_e32 v9, v21
	v_pk_add_f32 v[0:1], v[8:9], v[0:1]
	v_mov_b32_e32 v31, v20
	v_pk_add_f32 v[0:1], v[30:31], v[0:1]
	ds_bpermute_b32 v9, v221, v1
	ds_bpermute_b32 v8, v221, v0
	s_waitcnt lgkmcnt(0)
	v_pk_add_f32 v[0:1], v[0:1], v[8:9]
	ds_bpermute_b32 v9, v220, v1
	ds_bpermute_b32 v8, v220, v0
	s_waitcnt lgkmcnt(0)
	v_pk_add_f32 v[0:1], v[0:1], v[8:9]
	ds_bpermute_b32 v9, v219, v1
	ds_bpermute_b32 v8, v219, v0
	s_waitcnt lgkmcnt(0)
	v_pk_add_f32 v[0:1], v[0:1], v[8:9]
	ds_bpermute_b32 v9, v218, v1
	ds_bpermute_b32 v8, v218, v0
	s_waitcnt lgkmcnt(0)
; DEV bf16_t f2bf(float f) { unsigned u = __float_as_uint(f); u += 0x7fffu + ((u >> 16) & 1u); return (bf16_t)(u >> 16); }
; DEV void attn_store16(f32x4 (&o)[2][8], const float* __restrict__ gain, float oscale, bf16_t* __restrict__ mix, int q0, int colbase) {
;     ...
;   for (int g = 0; g < 2; ++g)
; #pragma unroll
;     for (int j = 0; j < 4; ++j) {
;       float ss = 0.f;
; #pragma unroll
;       for (int cb = 0; cb < 8; ++cb) ss += o[g][cb][j] * o[g][cb][j];
;       ss += __shfl_xor(ss, 1); ss += __shfl_xor(ss, 2); ss += __shfl_xor(ss, 4); ss += __shfl_xor(ss, 8);
;       const float rn = rsqrtf(ss * (1.f / 128.f) + EPS);
;       const int sl = 16 * g + 4 * fq + j;
; #pragma unroll
;       for (int cb = 0; cb < 8; ++cb) *reinterpret_cast<bf16_t*>(sc + sl * 272 + (16 * cb + fr) * 2) = f2bf(o[g][cb][j] * rn * gn[cb]);
;     }
; #pragma unroll
;   for (int i = 0; i < 8; ++i) { const int rs = 4 * i + (lane >> 4);
;     const u32x4 w = *reinterpret_cast<const u32x4*>(sc + rs * 272 + (lane & 15) * 16);
;     const size_t row = (size_t)(q0 + 64 * (rs >> 3) + 8 * wid + (rs & 7));
;     *reinterpret_cast<u32x4*>(mix + row * DM + colbase + (lane & 15) * 8) = w; }
;   __syncthreads();
; }
	v_pk_add_f32 v[0:1], v[0:1], v[8:9]
	s_nop 0
	v_pk_fma_f32 v[0:1], v[0:1], s[4:5], v[22:23] op_sel_hi:[1,0,0]
	s_nop 0
	v_mul_f32_e32 v8, 0x4b800000, v1
	v_cmp_gt_f32_e64 s[0:1], s33, v1
	v_cmp_gt_f32_e32 vcc, s33, v0
	s_nop 0
	v_cndmask_b32_e64 v1, v1, v8, s[0:1]
	v_rsq_f32_e32 v1, v1
	s_nop 0
	v_mul_f32_e32 v8, 0x45800000, v1
	v_cndmask_b32_e64 v1, v1, v8, s[0:1]
	v_mul_f32_e32 v6, v6, v1
	v_mul_f32_e32 v6, v49, v6
	v_bfe_u32 v8, v6, 16, 1
	v_mul_f32_e32 v4, v4, v1
	v_add3_u32 v6, v6, v8, s2
	v_mul_f32_e32 v4, v50, v4
	ds_write_b16_d16_hi v70, v6 offset:4896
	v_bfe_u32 v6, v4, 16, 1
	v_add3_u32 v4, v4, v6, s2
	ds_write_b16_d16_hi v70, v4 offset:4928
	v_mul_f32_e32 v4, v14, v1
	v_mul_f32_e32 v4, v51, v4
	v_bfe_u32 v6, v4, 16, 1
	v_add3_u32 v4, v4, v6, s2
	ds_write_b16_d16_hi v70, v4 offset:4960
	v_mul_f32_e32 v4, v12, v1
	v_mul_f32_e32 v4, v56, v4
	v_bfe_u32 v6, v4, 16, 1
	v_add3_u32 v4, v4, v6, s2
	ds_write_b16_d16_hi v70, v4 offset:4992
	v_mul_f32_e32 v4, v18, v1
	v_mul_f32_e32 v4, v58, v4
	v_bfe_u32 v6, v4, 16, 1
	v_add3_u32 v4, v4, v6, s2
	ds_write_b16_d16_hi v70, v4 offset:5024
	v_mul_f32_e32 v4, v16, v1
	v_mul_f32_e32 v4, v59, v4
	v_bfe_u32 v6, v4, 16, 1
	v_add3_u32 v4, v4, v6, s2
	ds_write_b16_d16_hi v70, v4 offset:5056
	v_mul_f32_e32 v4, v10, v1
	v_mul_f32_e32 v1, v2, v1
	v_mul_f32_e32 v1, v69, v1
	v_bfe_u32 v2, v1, 16, 1
	v_add3_u32 v1, v1, v2, s2
	ds_write_b16_d16_hi v70, v1 offset:5120
	v_mul_f32_e32 v1, 0x4b800000, v0
	v_cndmask_b32_e32 v0, v0, v1, vcc
	v_rsq_f32_e32 v0, v0
	v_mul_f32_e32 v4, v68, v4
	v_bfe_u32 v6, v4, 16, 1
	v_add3_u32 v4, v4, v6, s2
	v_mul_f32_e32 v1, 0x45800000, v0
	v_cndmask_b32_e32 v0, v0, v1, vcc
	v_mul_f32_e32 v1, v7, v0
	v_mul_f32_e32 v1, v49, v1
	v_bfe_u32 v2, v1, 16, 1
	v_add3_u32 v1, v1, v2, s2
	ds_write_b16_d16_hi v70, v1 offset:5168
	v_mul_f32_e32 v1, v5, v0
	v_mul_f32_e32 v1, v50, v1
	v_bfe_u32 v2, v1, 16, 1
	v_add3_u32 v1, v1, v2, s2
	ds_write_b16_d16_hi v70, v1 offset:5200
	v_mul_f32_e32 v1, v15, v0
	v_mul_f32_e32 v1, v51, v1
	v_bfe_u32 v2, v1, 16, 1
	v_add3_u32 v1, v1, v2, s2
	ds_write_b16_d16_hi v70, v1 offset:5232
	v_mul_f32_e32 v1, v13, v0
	v_mul_f32_e32 v1, v56, v1
	v_bfe_u32 v2, v1, 16, 1
	v_add3_u32 v1, v1, v2, s2
	ds_write_b16_d16_hi v70, v1 offset:5264
	v_mul_f32_e32 v1, v19, v0
	v_mul_f32_e32 v1, v58, v1
	v_bfe_u32 v2, v1, 16, 1
	v_add3_u32 v1, v1, v2, s2
	ds_write_b16_d16_hi v70, v1 offset:5296
	v_mul_f32_e32 v1, v17, v0
	v_mul_f32_e32 v1, v59, v1
	v_bfe_u32 v2, v1, 16, 1
	v_add3_u32 v1, v1, v2, s2
	ds_write_b16_d16_hi v70, v1 offset:5328
	v_mul_f32_e32 v1, v11, v0
	v_mul_f32_e32 v1, v68, v1
	v_bfe_u32 v2, v1, 16, 1
	v_mul_f32_e32 v0, v3, v0
	v_add3_u32 v1, v1, v2, s2
	v_mul_f32_e32 v0, v69, v0
	ds_write_b16_d16_hi v70, v1 offset:5360
	v_bfe_u32 v1, v0, 16, 1
	v_add3_u32 v0, v0, v1, s2
	ds_write_b16_d16_hi v70, v0 offset:5392
	v_mul_u32_u24_e32 v0, 0x110, v42
	ds_write_b16_d16_hi v70, v4 offset:5088
	v_add3_u32 v9, v57, v192, v0
	v_lshl_add_u32 v8, v43, 3, s74
	ds_read_b128 v[0:3], v9
	v_readlane_b32 s0, v255, 47
	v_or_b32_e32 v6, v8, v42
	v_readlane_b32 s1, v255, 48
	v_ashrrev_i32_e32 v7, 31, v6
	v_lshlrev_b64 v[6:7], 12, v[6:7]
	v_lshl_add_u64 v[4:5], s[0:1], 0, v[192:193]
	v_lshl_add_u64 v[6:7], v[4:5], 0, v[6:7]
	s_waitcnt lgkmcnt(0)
	global_store_dwordx4 v[6:7], v[0:3], off offset:2048
	v_or_b32_e32 v10, 4, v42
	ds_read_b128 v[0:3], v9 offset:1088
	v_or_b32_e32 v6, v8, v10
	v_ashrrev_i32_e32 v7, 31, v6
	v_lshlrev_b64 v[6:7], 12, v[6:7]
	v_lshl_add_u64 v[6:7], v[4:5], 0, v[6:7]
	s_waitcnt lgkmcnt(0)
	global_store_dwordx4 v[6:7], v[0:3], off offset:2048
	ds_read_b128 v[0:3], v9 offset:2176
	v_add_u32_e32 v11, 64, v8
	v_or_b32_e32 v6, v11, v42
	v_ashrrev_i32_e32 v7, 31, v6
	v_lshlrev_b64 v[6:7], 12, v[6:7]
	v_lshl_add_u64 v[6:7], v[4:5], 0, v[6:7]
	s_waitcnt lgkmcnt(0)
	global_store_dwordx4 v[6:7], v[0:3], off offset:2048
	ds_read_b128 v[0:3], v9 offset:3264
	v_or_b32_e32 v6, v11, v10
	v_ashrrev_i32_e32 v7, 31, v6
	v_lshlrev_b64 v[6:7], 12, v[6:7]
	v_lshl_add_u64 v[6:7], v[4:5], 0, v[6:7]
	s_waitcnt lgkmcnt(0)
	global_store_dwordx4 v[6:7], v[0:3], off offset:2048
	ds_read_b128 v[0:3], v9 offset:4352
	v_add_u32_e32 v11, 0x80, v8
	v_or_b32_e32 v6, v11, v42
	v_ashrrev_i32_e32 v7, 31, v6
	v_lshlrev_b64 v[6:7], 12, v[6:7]
	v_lshl_add_u64 v[6:7], v[4:5], 0, v[6:7]
	s_waitcnt lgkmcnt(0)
	global_store_dwordx4 v[6:7], v[0:3], off offset:2048
	ds_read_b128 v[0:3], v9 offset:5440
	v_or_b32_e32 v6, v11, v10
	v_ashrrev_i32_e32 v7, 31, v6
	v_lshlrev_b64 v[6:7], 12, v[6:7]
	v_lshl_add_u64 v[6:7], v[4:5], 0, v[6:7]
	s_waitcnt lgkmcnt(0)
	global_store_dwordx4 v[6:7], v[0:3], off offset:2048
	ds_read_b128 v[0:3], v9 offset:6528
	v_add_u32_e32 v8, 0xc0, v8
	v_or_b32_e32 v6, v8, v42
	v_ashrrev_i32_e32 v7, 31, v6
	v_lshlrev_b64 v[6:7], 12, v[6:7]
	v_lshl_add_u64 v[6:7], v[4:5], 0, v[6:7]
	s_waitcnt lgkmcnt(0)
	global_store_dwordx4 v[6:7], v[0:3], off offset:2048
	ds_read_b128 v[0:3], v9 offset:7616
	v_or_b32_e32 v6, v8, v10
	v_ashrrev_i32_e32 v7, 31, v6
	v_lshlrev_b64 v[6:7], 12, v[6:7]
	v_lshl_add_u64 v[4:5], v[4:5], 0, v[6:7]
	s_mov_b64 s[0:1], 0
	s_and_b64 vcc, exec, s[8:9]
	s_waitcnt lgkmcnt(0)
	global_store_dwordx4 v[4:5], v[0:3], off offset:2048
	s_barrier
	s_cbranch_vccz .LBB0_351
	s_branch .LBB0_349

; #define DECODE(Lx, PM, PN) do { int wgid = (Lx); \
;     { int q = nwg / NXCD, r = nwg % NXCD, xcd = wgid % NXCD, off = wgid / NXCD; wgid = (xcd < r ? xcd * (q + 1) : r * (q + 1) + (xcd - r) * q) + off; } \
;     const int nig = WGM * nN, gid = wgid / nig, fm = gid * WGM, gsz = min(nM - fm, WGM); \
;     PM = fm + ((wgid % nig) % gsz); PN = (wgid % nig) / gsz; } while (0)
; template <int MODE>
; DEV void gemm_phase(const bf16_t* __restrict__ A, const bf16_t* __restrict__ Bt, int M, int N, int K, bf16_t* __restrict__ Out, int ldo,
;                     const float* __restrict__ rstd, const float* __restrict__ rope) {
;     ...
;     const bool has_next = (L + (int)gridDim.x) < nwg;
;     int npm = pm, npn = pn; if (has_next) DECODE(L + (int)gridDim.x, npm, npn);
;     const char* nA = (const char*)A + (size_t)npm * tstep; const char* nB = (const char*)Bt + (size_t)npn * tstep;
;     const int brow = pm * BM, bcol = pn * BM;
;     ...
; #pragma unroll
;     for (int a = 0; a < 2; ++a)
; #pragma unroll
;       for (int b = 0; b < 2; ++b)
; #pragma unroll
;         for (int m = 0; m < 4; ++m)
; #pragma unroll
;           for (int n = 0; n < 2; ++n) acc[a][b][m][n] = (f32x4){0.f, 0.f, 0.f, 0.f};
;     pm = npm; pn = npn; cA = nA; cB = nB; L += (int)gridDim.x;
.LBB0_492:
	s_ashr_i32 s11, s10, 31
	s_lshl_b64 s[14:15], s[10:11], 20
	s_add_u32 s14, s56, s14
	s_addc_u32 s15, s57, s15
	s_ashr_i32 s13, s12, 31
	s_lshl_b64 s[16:17], s[12:13], 20
	s_add_u32 s11, s74, s16
	s_addc_u32 s13, s75, s17
	s_add_u32 s18, s18, 0x80080
	s_addc_u32 s19, s19, 0
	v_readlane_b32 s22, v255, 1
	s_add_u32 s36, s22, s20
	v_readlane_b32 s20, v255, 2
	v_mov_b32_e32 v0, 0
	s_addc_u32 s37, s20, s21
	s_mov_b32 s38, -2
	v_mov_b32_e32 v1, v0
	v_mov_b32_e32 v2, v0
	v_mov_b32_e32 v3, v0
	v_mov_b32_e32 v4, v0
	v_mov_b32_e32 v5, v0
	v_mov_b32_e32 v6, v0
	v_mov_b32_e32 v7, v0
	v_mov_b32_e32 v8, v0
	v_mov_b32_e32 v9, v0
	v_mov_b32_e32 v10, v0
	v_mov_b32_e32 v11, v0
	v_mov_b32_e32 v12, v0
	v_mov_b32_e32 v13, v0
	v_mov_b32_e32 v14, v0
	v_mov_b32_e32 v15, v0
	v_mov_b32_e32 v24, v0
	v_mov_b32_e32 v25, v0
	v_mov_b32_e32 v26, v0
	v_mov_b32_e32 v27, v0
	v_mov_b32_e32 v28, v0
	v_mov_b32_e32 v29, v0
	v_mov_b32_e32 v30, v0
	v_mov_b32_e32 v31, v0
	v_mov_b32_e32 v40, v0
	v_mov_b32_e32 v41, v0
	v_mov_b32_e32 v42, v0
	v_mov_b32_e32 v43, v0
	v_mov_b32_e32 v44, v0
	v_mov_b32_e32 v45, v0
	v_mov_b32_e32 v46, v0
	v_mov_b32_e32 v47, v0
	v_mov_b32_e32 v16, v0
	v_mov_b32_e32 v17, v0
	v_mov_b32_e32 v18, v0
	v_mov_b32_e32 v19, v0
	v_mov_b32_e32 v20, v0
	v_mov_b32_e32 v21, v0
	v_mov_b32_e32 v22, v0
	v_mov_b32_e32 v23, v0
	v_mov_b32_e32 v32, v0
	v_mov_b32_e32 v33, v0
	v_mov_b32_e32 v34, v0
	v_mov_b32_e32 v35, v0
	v_mov_b32_e32 v36, v0
	v_mov_b32_e32 v37, v0
	v_mov_b32_e32 v38, v0
	v_mov_b32_e32 v39, v0
	v_mov_b32_e32 v48, v0
	v_mov_b32_e32 v49, v0
	v_mov_b32_e32 v50, v0
	v_mov_b32_e32 v51, v0
	v_mov_b32_e32 v52, v0
	v_mov_b32_e32 v53, v0
	v_mov_b32_e32 v54, v0
	v_mov_b32_e32 v55, v0
	v_mov_b32_e32 v56, v0
	v_mov_b32_e32 v57, v0
	v_mov_b32_e32 v58, v0
	v_mov_b32_e32 v59, v0
	v_mov_b32_e32 v60, v0
	v_mov_b32_e32 v61, v0
	v_mov_b32_e32 v62, v0
	v_mov_b32_e32 v63, v0
	v_mov_b32_e32 v64, v0
	v_mov_b32_e32 v65, v0
	v_mov_b32_e32 v66, v0
	v_mov_b32_e32 v67, v0
	v_mov_b32_e32 v68, v0
	v_mov_b32_e32 v69, v0
	v_mov_b32_e32 v70, v0
	v_mov_b32_e32 v71, v0
	v_mov_b32_e32 v72, v0
	v_mov_b32_e32 v73, v0
	v_mov_b32_e32 v74, v0
	v_mov_b32_e32 v75, v0
	v_mov_b32_e32 v76, v0
	v_mov_b32_e32 v77, v0
	v_mov_b32_e32 v78, v0
	v_mov_b32_e32 v79, v0
	v_mov_b32_e32 v88, v0
	v_mov_b32_e32 v89, v0
	v_mov_b32_e32 v90, v0
	v_mov_b32_e32 v91, v0
	v_mov_b32_e32 v92, v0
	v_mov_b32_e32 v93, v0
	v_mov_b32_e32 v94, v0
	v_mov_b32_e32 v95, v0
	v_mov_b32_e32 v104, v0
	v_mov_b32_e32 v105, v0
	v_mov_b32_e32 v106, v0
	v_mov_b32_e32 v107, v0
	v_mov_b32_e32 v108, v0
	v_mov_b32_e32 v109, v0
	v_mov_b32_e32 v110, v0
	v_mov_b32_e32 v111, v0
	v_mov_b32_e32 v80, v0
	v_mov_b32_e32 v81, v0
	v_mov_b32_e32 v82, v0
	v_mov_b32_e32 v83, v0
	v_mov_b32_e32 v84, v0
	v_mov_b32_e32 v85, v0
	v_mov_b32_e32 v86, v0
	v_mov_b32_e32 v87, v0
	v_mov_b32_e32 v96, v0
	v_mov_b32_e32 v97, v0
	v_mov_b32_e32 v98, v0
	v_mov_b32_e32 v99, v0
	v_mov_b32_e32 v100, v0
	v_mov_b32_e32 v101, v0
	v_mov_b32_e32 v102, v0
	v_mov_b32_e32 v103, v0
	v_mov_b32_e32 v112, v0
	v_mov_b32_e32 v113, v0
	v_mov_b32_e32 v114, v0
	v_mov_b32_e32 v115, v0
	v_mov_b32_e32 v116, v0
	v_mov_b32_e32 v117, v0
	v_mov_b32_e32 v118, v0
	v_mov_b32_e32 v119, v0
	v_mov_b32_e32 v120, v0
	v_mov_b32_e32 v121, v0
	v_mov_b32_e32 v122, v0
	v_mov_b32_e32 v123, v0
	v_mov_b32_e32 v124, v0
	v_mov_b32_e32 v125, v0
	v_mov_b32_e32 v126, v0
	v_mov_b32_e32 v127, v0
	s_mov_b64 s[44:45], 0x80
	.p2align 6

; #define DECODE(Lx, PM, PN) do { int wgid = (Lx); \
;     { int q = nwg / NXCD, r = nwg % NXCD, xcd = wgid % NXCD, off = wgid / NXCD; wgid = (xcd < r ? xcd * (q + 1) : r * (q + 1) + (xcd - r) * q) + off; } \
;     const int nig = WGM * nN, gid = wgid / nig, fm = gid * WGM, gsz = min(nM - fm, WGM); \
;     PM = fm + ((wgid % nig) % gsz); PN = (wgid % nig) / gsz; } while (0)
; template <int MODE>
; DEV void gemm_phase(const bf16_t* __restrict__ A, const bf16_t* __restrict__ Bt, int M, int N, int K, bf16_t* __restrict__ Out, int ldo,
;                     const float* __restrict__ rstd, const float* __restrict__ rope) {
;     ...
;     const bool has_next = (L + (int)gridDim.x) < nwg;
;     int npm = pm, npn = pn; if (has_next) DECODE(L + (int)gridDim.x, npm, npn);
;     const char* nA = (const char*)A + (size_t)npm * tstep; const char* nB = (const char*)Bt + (size_t)npn * tstep;
;     const int brow = pm * BM, bcol = pn * BM;
;     ...
; #pragma unroll
;     for (int a = 0; a < 2; ++a)
; #pragma unroll
;       for (int b = 0; b < 2; ++b)
; #pragma unroll
;         for (int m = 0; m < 4; ++m)
; #pragma unroll
;           for (int n = 0; n < 2; ++n) acc[a][b][m][n] = (f32x4){0.f, 0.f, 0.f, 0.f};
;     pm = npm; pn = npn; cA = nA; cB = nB; L += (int)gridDim.x;
.LBB0_617:
	s_ashr_i32 s9, s8, 31
	s_lshl_b64 s[14:15], s[8:9], 20
	s_add_u32 s9, s66, s14
	s_addc_u32 s36, s67, s15
	s_ashr_i32 s11, s10, 31
	s_lshl_b64 s[16:17], s[10:11], 20
	s_add_u32 s11, s78, s16
	s_addc_u32 s37, s79, s17
	s_add_u32 s38, s58, s20
	s_addc_u32 s39, s59, s21
	v_lshl_add_u64 v[140:141], v[136:137], 0, s[20:21]
	v_lshl_add_u64 v[142:143], v[138:139], 0, s[20:21]
	v_readlane_b32 s20, v255, 3
	s_add_u32 s40, s20, s18
	v_readlane_b32 s18, v255, 4
	v_mov_b32_e32 v0, 0
	s_addc_u32 s41, s18, s19
	s_mov_b32 s42, -2
	s_mov_b64 s[18:19], 0
	v_mov_b32_e32 v1, v0
	v_mov_b32_e32 v2, v0
	v_mov_b32_e32 v3, v0
	v_mov_b32_e32 v8, v0
	v_mov_b32_e32 v9, v0
	v_mov_b32_e32 v10, v0
	v_mov_b32_e32 v11, v0
	v_mov_b32_e32 v16, v0
	v_mov_b32_e32 v17, v0
	v_mov_b32_e32 v18, v0
	v_mov_b32_e32 v19, v0
	v_mov_b32_e32 v20, v0
	v_mov_b32_e32 v21, v0
	v_mov_b32_e32 v22, v0
	v_mov_b32_e32 v23, v0
	v_mov_b32_e32 v32, v0
	v_mov_b32_e32 v33, v0
	v_mov_b32_e32 v34, v0
	v_mov_b32_e32 v35, v0
	v_mov_b32_e32 v36, v0
	v_mov_b32_e32 v37, v0
	v_mov_b32_e32 v38, v0
	v_mov_b32_e32 v39, v0
	v_mov_b32_e32 v48, v0
	v_mov_b32_e32 v49, v0
	v_mov_b32_e32 v50, v0
	v_mov_b32_e32 v51, v0
	v_mov_b32_e32 v52, v0
	v_mov_b32_e32 v53, v0
	v_mov_b32_e32 v54, v0
	v_mov_b32_e32 v55, v0
	v_mov_b32_e32 v4, v0
	v_mov_b32_e32 v5, v0
	v_mov_b32_e32 v6, v0
	v_mov_b32_e32 v7, v0
	v_mov_b32_e32 v12, v0
	v_mov_b32_e32 v13, v0
	v_mov_b32_e32 v14, v0
	v_mov_b32_e32 v15, v0
	v_mov_b32_e32 v24, v0
	v_mov_b32_e32 v25, v0
	v_mov_b32_e32 v26, v0
	v_mov_b32_e32 v27, v0
	v_mov_b32_e32 v28, v0
	v_mov_b32_e32 v29, v0
	v_mov_b32_e32 v30, v0
	v_mov_b32_e32 v31, v0
	v_mov_b32_e32 v40, v0
	v_mov_b32_e32 v41, v0
	v_mov_b32_e32 v42, v0
	v_mov_b32_e32 v43, v0
	v_mov_b32_e32 v44, v0
	v_mov_b32_e32 v45, v0
	v_mov_b32_e32 v46, v0
	v_mov_b32_e32 v47, v0
	v_mov_b32_e32 v56, v0
	v_mov_b32_e32 v57, v0
	v_mov_b32_e32 v58, v0
	v_mov_b32_e32 v59, v0
	v_mov_b32_e32 v60, v0
	v_mov_b32_e32 v61, v0
	v_mov_b32_e32 v62, v0
	v_mov_b32_e32 v63, v0
	v_mov_b32_e32 v64, v0
	v_mov_b32_e32 v65, v0
	v_mov_b32_e32 v66, v0
	v_mov_b32_e32 v67, v0
	v_mov_b32_e32 v68, v0
	v_mov_b32_e32 v69, v0
	v_mov_b32_e32 v70, v0
	v_mov_b32_e32 v71, v0
	v_mov_b32_e32 v80, v0
	v_mov_b32_e32 v81, v0
	v_mov_b32_e32 v82, v0
	v_mov_b32_e32 v83, v0
	v_mov_b32_e32 v84, v0
	v_mov_b32_e32 v85, v0
	v_mov_b32_e32 v86, v0
	v_mov_b32_e32 v87, v0
	v_mov_b32_e32 v96, v0
	v_mov_b32_e32 v97, v0
	v_mov_b32_e32 v98, v0
	v_mov_b32_e32 v99, v0
	v_mov_b32_e32 v100, v0
	v_mov_b32_e32 v101, v0
	v_mov_b32_e32 v102, v0
	v_mov_b32_e32 v103, v0
	v_mov_b32_e32 v112, v0
	v_mov_b32_e32 v113, v0
	v_mov_b32_e32 v114, v0
	v_mov_b32_e32 v115, v0
	v_mov_b32_e32 v116, v0
	v_mov_b32_e32 v117, v0
	v_mov_b32_e32 v118, v0
	v_mov_b32_e32 v119, v0
	v_mov_b32_e32 v72, v0
	v_mov_b32_e32 v73, v0
	v_mov_b32_e32 v74, v0
	v_mov_b32_e32 v75, v0
	v_mov_b32_e32 v76, v0
	v_mov_b32_e32 v77, v0
	v_mov_b32_e32 v78, v0
	v_mov_b32_e32 v79, v0
	v_mov_b32_e32 v88, v0
	v_mov_b32_e32 v89, v0
	v_mov_b32_e32 v90, v0
	v_mov_b32_e32 v91, v0
	v_mov_b32_e32 v92, v0
	v_mov_b32_e32 v93, v0
	v_mov_b32_e32 v94, v0
	v_mov_b32_e32 v95, v0
	v_mov_b32_e32 v104, v0
	v_mov_b32_e32 v105, v0
	v_mov_b32_e32 v106, v0
	v_mov_b32_e32 v107, v0
	v_mov_b32_e32 v108, v0
	v_mov_b32_e32 v109, v0
	v_mov_b32_e32 v110, v0
	v_mov_b32_e32 v111, v0
	v_mov_b32_e32 v120, v0
	v_mov_b32_e32 v121, v0
	v_mov_b32_e32 v122, v0
	v_mov_b32_e32 v123, v0
	v_mov_b32_e32 v124, v0
	v_mov_b32_e32 v125, v0
	v_mov_b32_e32 v126, v0
	v_mov_b32_e32 v127, v0
	s_mov_b64 s[46:47], 0x80
	.p2align 6

; #define DECODE(Lx, PM, PN) do { int wgid = (Lx); \
;     { int q = nwg / NXCD, r = nwg % NXCD, xcd = wgid % NXCD, off = wgid / NXCD; wgid = (xcd < r ? xcd * (q + 1) : r * (q + 1) + (xcd - r) * q) + off; } \
;     const int nig = WGM * nN, gid = wgid / nig, fm = gid * WGM, gsz = min(nM - fm, WGM); \
;     PM = fm + ((wgid % nig) % gsz); PN = (wgid % nig) / gsz; } while (0)
; template <int MODE>
; DEV void gemm_phase(const bf16_t* __restrict__ A, const bf16_t* __restrict__ Bt, int M, int N, int K, bf16_t* __restrict__ Out, int ldo,
;                     const float* __restrict__ rstd, const float* __restrict__ rope) {
;     ...
;     const bool has_next = (L + (int)gridDim.x) < nwg;
;     int npm = pm, npn = pn; if (has_next) DECODE(L + (int)gridDim.x, npm, npn);
;     const char* nA = (const char*)A + (size_t)npm * tstep; const char* nB = (const char*)Bt + (size_t)npn * tstep;
;     const int brow = pm * BM, bcol = pn * BM;
;     ...
; #pragma unroll
;     for (int a = 0; a < 2; ++a)
; #pragma unroll
;       for (int b = 0; b < 2; ++b)
; #pragma unroll
;         for (int m = 0; m < 4; ++m)
; #pragma unroll
;           for (int n = 0; n < 2; ++n) acc[a][b][m][n] = (f32x4){0.f, 0.f, 0.f, 0.f};
;     pm = npm; pn = npn; cA = nA; cB = nB; L += (int)gridDim.x;
.LBB0_689:
	s_mul_i32 s8, s28, 0x2c0000
	s_mul_hi_i32 s9, s28, 0x2c0000
	s_add_u32 s8, s86, s8
	s_addc_u32 s9, s87, s9
	s_mul_i32 s10, s29, 0x2c0000
	s_mul_hi_i32 s11, s29, 0x2c0000
	s_add_u32 s34, s82, s10
	s_addc_u32 s35, s83, s11
	v_readlane_b32 s16, v255, 5
	s_add_u32 s36, s16, s14
	v_readlane_b32 s14, v255, 6
	v_mov_b32_e32 v0, 0
	s_addc_u32 s37, s14, s15
	s_mov_b32 s38, -2
	v_mov_b32_e32 v1, v0
	v_mov_b32_e32 v2, v0
	v_mov_b32_e32 v3, v0
	v_mov_b32_e32 v4, v0
	v_mov_b32_e32 v5, v0
	v_mov_b32_e32 v6, v0
	v_mov_b32_e32 v7, v0
	v_mov_b32_e32 v8, v0
	v_mov_b32_e32 v9, v0
	v_mov_b32_e32 v10, v0
	v_mov_b32_e32 v11, v0
	v_mov_b32_e32 v12, v0
	v_mov_b32_e32 v13, v0
	v_mov_b32_e32 v14, v0
	v_mov_b32_e32 v15, v0
	v_mov_b32_e32 v24, v0
	v_mov_b32_e32 v25, v0
	v_mov_b32_e32 v26, v0
	v_mov_b32_e32 v27, v0
	v_mov_b32_e32 v28, v0
	v_mov_b32_e32 v29, v0
	v_mov_b32_e32 v30, v0
	v_mov_b32_e32 v31, v0
	v_mov_b32_e32 v40, v0
	v_mov_b32_e32 v41, v0
	v_mov_b32_e32 v42, v0
	v_mov_b32_e32 v43, v0
	v_mov_b32_e32 v44, v0
	v_mov_b32_e32 v45, v0
	v_mov_b32_e32 v46, v0
	v_mov_b32_e32 v47, v0
	v_mov_b32_e32 v16, v0
	v_mov_b32_e32 v17, v0
	v_mov_b32_e32 v18, v0
	v_mov_b32_e32 v19, v0
	v_mov_b32_e32 v20, v0
	v_mov_b32_e32 v21, v0
	v_mov_b32_e32 v22, v0
	v_mov_b32_e32 v23, v0
	v_mov_b32_e32 v32, v0
	v_mov_b32_e32 v33, v0
	v_mov_b32_e32 v34, v0
	v_mov_b32_e32 v35, v0
	v_mov_b32_e32 v36, v0
	v_mov_b32_e32 v37, v0
	v_mov_b32_e32 v38, v0
	v_mov_b32_e32 v39, v0
	v_mov_b32_e32 v48, v0
	v_mov_b32_e32 v49, v0
	v_mov_b32_e32 v50, v0
	v_mov_b32_e32 v51, v0
	v_mov_b32_e32 v52, v0
	v_mov_b32_e32 v53, v0
	v_mov_b32_e32 v54, v0
	v_mov_b32_e32 v55, v0
	v_mov_b32_e32 v56, v0
	v_mov_b32_e32 v57, v0
	v_mov_b32_e32 v58, v0
	v_mov_b32_e32 v59, v0
	v_mov_b32_e32 v60, v0
	v_mov_b32_e32 v61, v0
	v_mov_b32_e32 v62, v0
	v_mov_b32_e32 v63, v0
	v_mov_b32_e32 v64, v0
	v_mov_b32_e32 v65, v0
	v_mov_b32_e32 v66, v0
	v_mov_b32_e32 v67, v0
	v_mov_b32_e32 v68, v0
	v_mov_b32_e32 v69, v0
	v_mov_b32_e32 v70, v0
	v_mov_b32_e32 v71, v0
	v_mov_b32_e32 v72, v0
	v_mov_b32_e32 v73, v0
	v_mov_b32_e32 v74, v0
	v_mov_b32_e32 v75, v0
	v_mov_b32_e32 v76, v0
	v_mov_b32_e32 v77, v0
	v_mov_b32_e32 v78, v0
	v_mov_b32_e32 v79, v0
	v_mov_b32_e32 v88, v0
	v_mov_b32_e32 v89, v0
	v_mov_b32_e32 v90, v0
	v_mov_b32_e32 v91, v0
	v_mov_b32_e32 v92, v0
	v_mov_b32_e32 v93, v0
	v_mov_b32_e32 v94, v0
	v_mov_b32_e32 v95, v0
	v_mov_b32_e32 v104, v0
	v_mov_b32_e32 v105, v0
	v_mov_b32_e32 v106, v0
	v_mov_b32_e32 v107, v0
	v_mov_b32_e32 v108, v0
	v_mov_b32_e32 v109, v0
	v_mov_b32_e32 v110, v0
	v_mov_b32_e32 v111, v0
	v_mov_b32_e32 v80, v0
	v_mov_b32_e32 v81, v0
	v_mov_b32_e32 v82, v0
	v_mov_b32_e32 v83, v0
	v_mov_b32_e32 v84, v0
	v_mov_b32_e32 v85, v0
	v_mov_b32_e32 v86, v0
	v_mov_b32_e32 v87, v0
	v_mov_b32_e32 v96, v0
	v_mov_b32_e32 v97, v0
	v_mov_b32_e32 v98, v0
	v_mov_b32_e32 v99, v0
	v_mov_b32_e32 v100, v0
	v_mov_b32_e32 v101, v0
	v_mov_b32_e32 v102, v0
	v_mov_b32_e32 v103, v0
	v_mov_b32_e32 v112, v0
	v_mov_b32_e32 v113, v0
	v_mov_b32_e32 v114, v0
	v_mov_b32_e32 v115, v0
	v_mov_b32_e32 v116, v0
	v_mov_b32_e32 v117, v0
	v_mov_b32_e32 v118, v0
	v_mov_b32_e32 v119, v0
	v_mov_b32_e32 v120, v0
	v_mov_b32_e32 v121, v0
	v_mov_b32_e32 v122, v0
	v_mov_b32_e32 v123, v0
	v_mov_b32_e32 v124, v0
	v_mov_b32_e32 v125, v0
	v_mov_b32_e32 v126, v0
	v_mov_b32_e32 v127, v0
	s_mov_b64 s[42:43], 0x80
	.p2align 6

; DEV unsigned cvtpk(float lo, float hi) { f32x2_t v = {lo, hi}; bf16x2_t b = __builtin_convertvector(v, bf16x2_t); return __builtin_bit_cast(unsigned, b); }
; DEV float wave_sum(float v) { for (int o = 32; o >= 1; o >>= 1) v += __shfl_xor(v, o); return v; }
; DEV void post_rows(const Params& p, const float* __restrict__ xsrc, const float* __restrict__ g, bool final) {
;     ...
;     for (int c = 0; c < 4; ++c) { const int idx = c * 512 + lane * 8; const u32x4 w = *reinterpret_cast<const u32x4*>(mb + (size_t)row * DM + idx);
; #pragma unroll
;       for (int e = 0; e < 4; ++e) { const float lo = __uint_as_float(w[e] << 16), hi = __uint_as_float(w[e] & 0xffff0000u);
;         mv[c * 8 + 2 * e] = lo; mv[c * 8 + 2 * e + 1] = hi; ss += lo * lo + hi * hi; } }
;     ss = wave_sum(ss);
;     const float rm = rsqrtf(ss * (1.f / DM) + EPS);
;     float sx = 0;
; #pragma unroll
;     for (int c = 0; c < 4; ++c) { const int idx = c * 512 + lane * 8;
;       float xo[8];
;       if (xsrc) { const f32x4 a = *reinterpret_cast<const f32x4*>(xsrc + (size_t)row * DM + idx), b = *reinterpret_cast<const f32x4*>(xsrc + (size_t)row * DM + idx + 4);
; #pragma unroll
;         for (int e = 0; e < 4; ++e) { xo[e] = a[e]; xo[4 + e] = b[e]; } }
;       else { const u32x4 w = *reinterpret_cast<const u32x4*>(xb + (size_t)row * DM + idx);
; #pragma unroll
;         for (int e = 0; e < 4; ++e) { xo[2 * e] = __uint_as_float(w[e] << 16); xo[2 * e + 1] = __uint_as_float(w[e] & 0xffff0000u); } }
;       const f32x4 g0 = *reinterpret_cast<const f32x4*>(g + idx), g1 = *reinterpret_cast<const f32x4*>(g + idx + 4);
;       float xn[8];
; #pragma unroll
;       for (int e = 0; e < 4; ++e) { xn[e] = xo[e] + mv[c * 8 + e] * rm * g0[e]; xn[4 + e] = xo[4 + e] + mv[c * 8 + 4 + e] * rm * g1[e]; }
;       if (final) { *reinterpret_cast<f32x4*>(p.out + (size_t)row * DM + idx) = (f32x4){xn[0], xn[1], xn[2], xn[3]};
;                    *reinterpret_cast<f32x4*>(p.out + (size_t)row * DM + idx + 4) = (f32x4){xn[4], xn[5], xn[6], xn[7]}; }
;       else { const u32x4 w = {cvtpk(xn[0], xn[1]), cvtpk(xn[2], xn[3]), cvtpk(xn[4], xn[5]), cvtpk(xn[6], xn[7])};
;         *reinterpret_cast<u32x4*>(xb + (size_t)row * DM + idx) = w;
; #pragma unroll
;         for (int e = 0; e < 4; ++e) { const float lo = __uint_as_float(w[e] << 16), hi = __uint_as_float(w[e] & 0xffff0000u); sx += lo * lo + hi * hi; } } }
.LBB0_753:
	v_ashrrev_i32_e32 v41, 31, v40
	v_lshlrev_b64 v[52:53], 12, v[40:41]
	v_lshl_add_u64 v[54:55], v[44:45], 0, v[52:53]
	s_waitcnt lgkmcnt(0)
	global_load_dwordx4 v[32:35], v[54:55], off offset:1024
	global_load_dwordx4 v[36:39], v[54:55], off offset:2048
	global_load_dwordx4 v[56:59], v[54:55], off offset:3072
	global_load_dwordx4 v[86:89], v[54:55], off
	v_lshl_add_u64 v[52:53], v[46:47], 0, v[52:53]
	global_load_dwordx4 v[90:93], v[52:53], off
	global_load_dwordx4 v[116:119], v[52:53], off offset:1024
	global_load_dwordx4 v[120:123], v[52:53], off offset:2048
	global_load_dwordx4 v[124:127], v[52:53], off offset:3072
	v_readlane_b32 s0, v255, 40
	v_readlane_b32 s1, v255, 41
	s_and_b64 vcc, exec, s[0:1]
	s_mov_b64 s[6:7], -1
	s_waitcnt vmcnt(7)
	v_lshlrev_b32_e32 v84, 16, v34
	s_waitcnt vmcnt(6)
	v_lshlrev_b32_e32 v74, 16, v36
	v_and_b32_e32 v75, 0xffff0000, v36
	v_lshlrev_b32_e32 v70, 16, v37
	v_and_b32_e32 v71, 0xffff0000, v37
	v_lshlrev_b32_e32 v76, 16, v38
	v_and_b32_e32 v77, 0xffff0000, v38
	v_lshlrev_b32_e32 v72, 16, v39
	v_and_b32_e32 v73, 0xffff0000, v39
	s_waitcnt vmcnt(4)
	v_lshlrev_b32_e32 v36, 16, v87
	v_and_b32_e32 v37, 0xffff0000, v87
	v_lshlrev_b32_e32 v38, 16, v86
	v_and_b32_e32 v39, 0xffff0000, v86
	v_and_b32_e32 v85, 0xffff0000, v34
	v_lshlrev_b32_e32 v80, 16, v35
	v_and_b32_e32 v81, 0xffff0000, v35
	v_lshlrev_b32_e32 v34, 16, v88
	v_and_b32_e32 v35, 0xffff0000, v88
	v_pk_mul_f32 v[106:107], v[36:37], v[36:37]
	v_pk_mul_f32 v[108:109], v[38:39], v[38:39]
	v_lshlrev_b32_e32 v82, 16, v32
	v_and_b32_e32 v83, 0xffff0000, v32
	v_lshlrev_b32_e32 v78, 16, v33
	v_and_b32_e32 v79, 0xffff0000, v33
	v_and_b32_e32 v43, 0xffff0000, v57
	v_lshlrev_b32_e32 v32, 16, v89
	v_and_b32_e32 v33, 0xffff0000, v89
	v_pk_mul_f32 v[104:105], v[34:35], v[34:35]
	v_add_f32_e32 v49, v106, v107
	v_add_f32_e32 v61, v108, v109
	v_and_b32_e32 v65, 0xffff0000, v56
	v_and_b32_e32 v51, 0xffff0000, v59
	v_mov_b32_e32 v64, v43
	v_pk_mul_f32 v[102:103], v[32:33], v[32:33]
	v_add_f32_e32 v63, v104, v105
	v_add_f32_e32 v49, v61, v49
	v_and_b32_e32 v67, 0xffff0000, v58
	v_pk_mul_f32 v[54:55], v[82:83], v[82:83]
	v_mov_b32_e32 v66, v51
	v_pk_mul_f32 v[110:111], v[64:65], v[64:65]
	v_add_f32_e32 v64, v102, v103
	v_add_f32_e32 v49, v63, v49
	v_pk_mul_f32 v[68:69], v[78:79], v[78:79]
	v_pk_mul_f32 v[112:113], v[66:67], v[66:67]
	v_add_f32_e32 v66, v54, v55
	v_add_f32_e32 v49, v64, v49
	v_pk_mul_f32 v[86:87], v[84:85], v[84:85]
	v_add_f32_e32 v102, v68, v69
	v_add_f32_e32 v49, v66, v49
	v_pk_mul_f32 v[88:89], v[80:81], v[80:81]
	v_add_f32_e32 v86, v86, v87
	v_add_f32_e32 v49, v102, v49
	v_pk_mul_f32 v[94:95], v[74:75], v[74:75]
	v_add_f32_e32 v87, v88, v89
	v_add_f32_e32 v49, v86, v49
	v_pk_mul_f32 v[96:97], v[70:71], v[70:71]
	v_add_f32_e32 v88, v94, v95
	v_add_f32_e32 v49, v87, v49
	v_pk_mul_f32 v[98:99], v[76:77], v[76:77]
	v_add_f32_e32 v89, v96, v97
	v_add_f32_e32 v49, v88, v49
	v_lshlrev_b32_e32 v60, 16, v56
	v_pk_mul_f32 v[100:101], v[72:73], v[72:73]
	v_add_f32_e32 v94, v98, v99
	v_add_f32_e32 v49, v89, v49
	v_lshlrev_b32_e32 v56, 16, v57
	v_mov_b32_e32 v57, v60
	v_add_f32_e32 v95, v100, v101
	v_add_f32_e32 v49, v94, v49
	v_lshlrev_b32_e32 v62, 16, v58
	v_pk_fma_f32 v[54:55], v[56:57], v[56:57], v[110:111]
	v_add_f32_e32 v49, v95, v49
	v_lshlrev_b32_e32 v58, 16, v59
	v_mov_b32_e32 v59, v62
	v_add_f32_e32 v49, v55, v49
	v_pk_fma_f32 v[68:69], v[58:59], v[58:59], v[112:113]
	v_add_f32_e32 v49, v54, v49
	v_add_f32_e32 v49, v69, v49
	v_add_f32_e32 v49, v68, v49
	ds_bpermute_b32 v54, v216, v49
	s_waitcnt vmcnt(3)
	v_lshlrev_b32_e32 v86, 16, v92
	v_and_b32_e32 v87, 0xffff0000, v92
	v_lshlrev_b32_e32 v88, 16, v91
	v_and_b32_e32 v89, 0xffff0000, v91
	s_waitcnt lgkmcnt(0)
	v_add_f32_e32 v49, v49, v54
	ds_bpermute_b32 v54, v217, v49
	v_lshlrev_b32_e32 v92, 16, v90
	s_waitcnt lgkmcnt(0)
	v_add_f32_e32 v49, v49, v54
	ds_bpermute_b32 v54, v218, v49
	s_waitcnt lgkmcnt(0)
	v_add_f32_e32 v49, v49, v54
	ds_bpermute_b32 v54, v219, v49
	s_waitcnt lgkmcnt(0)
	v_add_f32_e32 v55, v49, v54
	ds_bpermute_b32 v57, v220, v55
	v_lshlrev_b32_e32 v54, 16, v93
	s_waitcnt lgkmcnt(0)
	v_add_f32_e32 v57, v55, v57
	ds_bpermute_b32 v59, v221, v57
	v_and_b32_e32 v55, 0xffff0000, v93
	v_and_b32_e32 v93, 0xffff0000, v90
	s_waitcnt lgkmcnt(0)
	v_add_f32_e32 v57, v57, v59
	v_mov_b32_e32 v59, 0x358637bd
	v_fmamk_f32 v57, v57, 0x3a000000, v59
	v_mul_f32_e32 v59, 0x4b800000, v57
	v_cmp_gt_f32_e64 s[0:1], s33, v57
	s_nop 1
	v_cndmask_b32_e64 v57, v57, v59, s[0:1]
	v_rsq_f32_e32 v57, v57
	s_nop 0
	v_mul_f32_e32 v59, 0x45800000, v57
	v_cndmask_b32_e64 v68, v57, v59, s[0:1]
	v_pk_mul_f32 v[38:39], v[68:69], v[38:39] op_sel_hi:[0,1]
	v_pk_mul_f32 v[34:35], v[68:69], v[34:35] op_sel_hi:[0,1]
	v_pk_mul_f32 v[90:91], v[68:69], v[36:37] op_sel_hi:[0,1]
	v_pk_mul_f32 v[94:95], v[68:69], v[32:33] op_sel_hi:[0,1]
	v_pk_fma_f32 v[36:37], v[0:1], v[38:39], v[92:93]
	v_pk_fma_f32 v[32:33], v[4:5], v[34:35], v[86:87]
	v_pk_fma_f32 v[38:39], v[2:3], v[90:91], v[88:89]
	v_pk_fma_f32 v[34:35], v[6:7], v[94:95], v[54:55]
	s_cbranch_vccz .LBB0_755
	v_cvt_pk_bf16_f32 v86, v36, v37
	v_cvt_pk_bf16_f32 v87, v38, v39
	v_cvt_pk_bf16_f32 v88, v32, v33
	v_cvt_pk_bf16_f32 v89, v34, v35
	global_store_dwordx4 v[52:53], v[86:89], off
	v_lshlrev_b32_e32 v55, 16, v87
	v_lshlrev_b32_e32 v54, 16, v86
	v_and_b32_e32 v87, 0xffff0000, v87
	v_and_b32_e32 v86, 0xffff0000, v86
	v_pk_mul_f32 v[86:87], v[86:87], v[86:87]
	s_mov_b64 s[6:7], 0
	v_pk_fma_f32 v[54:55], v[54:55], v[54:55], v[86:87]
	v_lshlrev_b32_e32 v87, 16, v89
	v_lshlrev_b32_e32 v86, 16, v88
	v_and_b32_e32 v89, 0xffff0000, v89
	v_and_b32_e32 v88, 0xffff0000, v88
	v_pk_mul_f32 v[88:89], v[88:89], v[88:89]
	v_add_f32_e32 v49, v54, v55
	v_pk_fma_f32 v[86:87], v[86:87], v[86:87], v[88:89]
	s_nop 0
	v_add_f32_e32 v49, v49, v86
	v_add_f32_e32 v49, v49, v87

; DEV unsigned cvtpk(float lo, float hi) { f32x2_t v = {lo, hi}; bf16x2_t b = __builtin_convertvector(v, bf16x2_t); return __builtin_bit_cast(unsigned, b); }
; DEV void post_rows(const Params& p, const float* __restrict__ xsrc, const float* __restrict__ g, bool final) {
;     ...
;     for (int c = 0; c < 4; ++c) { const int idx = c * 512 + lane * 8;
;       float xo[8];
;       if (xsrc) { const f32x4 a = *reinterpret_cast<const f32x4*>(xsrc + (size_t)row * DM + idx), b = *reinterpret_cast<const f32x4*>(xsrc + (size_t)row * DM + idx + 4);
; #pragma unroll
;         for (int e = 0; e < 4; ++e) { xo[e] = a[e]; xo[4 + e] = b[e]; } }
;       else { const u32x4 w = *reinterpret_cast<const u32x4*>(xb + (size_t)row * DM + idx);
; #pragma unroll
;         for (int e = 0; e < 4; ++e) { xo[2 * e] = __uint_as_float(w[e] << 16); xo[2 * e + 1] = __uint_as_float(w[e] & 0xffff0000u); } }
;       const f32x4 g0 = *reinterpret_cast<const f32x4*>(g + idx), g1 = *reinterpret_cast<const f32x4*>(g + idx + 4);
;       float xn[8];
; #pragma unroll
;       for (int e = 0; e < 4; ++e) { xn[e] = xo[e] + mv[c * 8 + e] * rm * g0[e]; xn[4 + e] = xo[4 + e] + mv[c * 8 + 4 + e] * rm * g1[e]; }
;       if (final) { *reinterpret_cast<f32x4*>(p.out + (size_t)row * DM + idx) = (f32x4){xn[0], xn[1], xn[2], xn[3]};
;                    *reinterpret_cast<f32x4*>(p.out + (size_t)row * DM + idx + 4) = (f32x4){xn[4], xn[5], xn[6], xn[7]}; }
;       else { const u32x4 w = {cvtpk(xn[0], xn[1]), cvtpk(xn[2], xn[3]), cvtpk(xn[4], xn[5]), cvtpk(xn[6], xn[7])};
;         *reinterpret_cast<u32x4*>(xb + (size_t)row * DM + idx) = w;
; #pragma unroll
;         for (int e = 0; e < 4; ++e) { const float lo = __uint_as_float(w[e] << 16), hi = __uint_as_float(w[e] & 0xffff0000u); sx += lo * lo + hi * hi; } } }
.LBB0_757:
	s_nop 0
	v_mov_b32_e32 v69, v68
	v_pk_mul_f32 v[32:33], v[68:69], v[82:83]
	v_pk_mul_f32 v[34:35], v[68:69], v[84:85]
	v_readlane_b32 s12, v255, 40
	v_readlane_b32 s13, v255, 41
	s_mov_b64 s[0:1], -1
	s_andn2_b64 vcc, exec, s[12:13]
	v_cndmask_b32_e64 v57, 0, 1, s[12:13]
	v_cmp_ne_u32_e64 s[6:7], 1, v57
	s_waitcnt vmcnt(3)
	v_lshlrev_b32_e32 v36, 16, v116
	v_and_b32_e32 v37, 0xffff0000, v116
	v_pk_fma_f32 v[36:37], v[8:9], v[32:33], v[36:37]
	v_lshlrev_b32_e32 v32, 16, v118
	v_and_b32_e32 v33, 0xffff0000, v118
	v_pk_fma_f32 v[32:33], v[12:13], v[34:35], v[32:33]
	v_pk_mul_f32 v[34:35], v[68:69], v[78:79]
	v_lshlrev_b32_e32 v38, 16, v117
	v_and_b32_e32 v39, 0xffff0000, v117
	v_pk_mul_f32 v[78:79], v[68:69], v[80:81]
	v_pk_fma_f32 v[38:39], v[10:11], v[34:35], v[38:39]
	v_lshlrev_b32_e32 v34, 16, v119
	v_and_b32_e32 v35, 0xffff0000, v119
	v_pk_fma_f32 v[34:35], v[14:15], v[78:79], v[34:35]
	s_cbranch_vccnz .LBB0_759
	v_cvt_pk_bf16_f32 v78, v36, v37
	v_cvt_pk_bf16_f32 v79, v38, v39
	v_cvt_pk_bf16_f32 v80, v32, v33
	v_cvt_pk_bf16_f32 v81, v34, v35
	global_store_dwordx4 v[52:53], v[78:81], off offset:1024
	v_lshlrev_b32_e32 v83, 16, v79
	v_lshlrev_b32_e32 v82, 16, v78
	v_and_b32_e32 v79, 0xffff0000, v79
	v_and_b32_e32 v78, 0xffff0000, v78
	v_pk_mul_f32 v[78:79], v[78:79], v[78:79]
	s_mov_b64 s[0:1], 0
	v_pk_fma_f32 v[78:79], v[82:83], v[82:83], v[78:79]
	s_nop 0
	v_add_f32_e32 v57, v49, v78
	v_add_f32_e32 v57, v57, v79
	v_lshlrev_b32_e32 v79, 16, v81
	v_lshlrev_b32_e32 v78, 16, v80
	v_and_b32_e32 v81, 0xffff0000, v81
	v_and_b32_e32 v80, 0xffff0000, v80
	v_pk_mul_f32 v[80:81], v[80:81], v[80:81]
	s_nop 0
	v_pk_fma_f32 v[78:79], v[78:79], v[78:79], v[80:81]
	s_nop 0
	v_add_f32_e32 v57, v57, v78
	v_add_f32_e32 v57, v57, v79

; DEV unsigned cvtpk(float lo, float hi) { f32x2_t v = {lo, hi}; bf16x2_t b = __builtin_convertvector(v, bf16x2_t); return __builtin_bit_cast(unsigned, b); }
; DEV void post_rows(const Params& p, const float* __restrict__ xsrc, const float* __restrict__ g, bool final) {
;     ...
;     for (int c = 0; c < 4; ++c) { const int idx = c * 512 + lane * 8;
;       float xo[8];
;       if (xsrc) { const f32x4 a = *reinterpret_cast<const f32x4*>(xsrc + (size_t)row * DM + idx), b = *reinterpret_cast<const f32x4*>(xsrc + (size_t)row * DM + idx + 4);
; #pragma unroll
;         for (int e = 0; e < 4; ++e) { xo[e] = a[e]; xo[4 + e] = b[e]; } }
;       else { const u32x4 w = *reinterpret_cast<const u32x4*>(xb + (size_t)row * DM + idx);
; #pragma unroll
;         for (int e = 0; e < 4; ++e) { xo[2 * e] = __uint_as_float(w[e] << 16); xo[2 * e + 1] = __uint_as_float(w[e] & 0xffff0000u); } }
;       const f32x4 g0 = *reinterpret_cast<const f32x4*>(g + idx), g1 = *reinterpret_cast<const f32x4*>(g + idx + 4);
;       float xn[8];
; #pragma unroll
;       for (int e = 0; e < 4; ++e) { xn[e] = xo[e] + mv[c * 8 + e] * rm * g0[e]; xn[4 + e] = xo[4 + e] + mv[c * 8 + 4 + e] * rm * g1[e]; }
;       if (final) { *reinterpret_cast<f32x4*>(p.out + (size_t)row * DM + idx) = (f32x4){xn[0], xn[1], xn[2], xn[3]};
;                    *reinterpret_cast<f32x4*>(p.out + (size_t)row * DM + idx + 4) = (f32x4){xn[4], xn[5], xn[6], xn[7]}; }
;       else { const u32x4 w = {cvtpk(xn[0], xn[1]), cvtpk(xn[2], xn[3]), cvtpk(xn[4], xn[5]), cvtpk(xn[6], xn[7])};
;         *reinterpret_cast<u32x4*>(xb + (size_t)row * DM + idx) = w;
; #pragma unroll
;         for (int e = 0; e < 4; ++e) { const float lo = __uint_as_float(w[e] << 16), hi = __uint_as_float(w[e] & 0xffff0000u); sx += lo * lo + hi * hi; } } }
.LBB0_761:
	s_nop 0
	s_nop 0
	v_pk_mul_f32 v[32:33], v[68:69], v[74:75]
	v_pk_mul_f32 v[34:35], v[68:69], v[76:77]
	s_mov_b64 s[0:1], -1
	s_and_b64 vcc, exec, s[6:7]
	s_waitcnt vmcnt(3)
	v_lshlrev_b32_e32 v36, 16, v120
	v_and_b32_e32 v37, 0xffff0000, v120
	v_pk_fma_f32 v[36:37], v[16:17], v[32:33], v[36:37]
	v_lshlrev_b32_e32 v32, 16, v122
	v_and_b32_e32 v33, 0xffff0000, v122
	v_pk_fma_f32 v[32:33], v[20:21], v[34:35], v[32:33]
	v_pk_mul_f32 v[34:35], v[68:69], v[70:71]
	v_lshlrev_b32_e32 v38, 16, v121
	v_and_b32_e32 v39, 0xffff0000, v121
	v_pk_mul_f32 v[70:71], v[68:69], v[72:73]
	v_pk_fma_f32 v[38:39], v[18:19], v[34:35], v[38:39]
	v_lshlrev_b32_e32 v34, 16, v123
	v_and_b32_e32 v35, 0xffff0000, v123
	v_pk_fma_f32 v[34:35], v[22:23], v[70:71], v[34:35]
	s_cbranch_vccnz .LBB0_763
	v_cvt_pk_bf16_f32 v70, v36, v37
	v_cvt_pk_bf16_f32 v71, v38, v39
	v_cvt_pk_bf16_f32 v72, v32, v33
	v_cvt_pk_bf16_f32 v73, v34, v35
	global_store_dwordx4 v[52:53], v[70:73], off offset:2048
	v_lshlrev_b32_e32 v75, 16, v71
	v_lshlrev_b32_e32 v74, 16, v70
	v_and_b32_e32 v71, 0xffff0000, v71
	v_and_b32_e32 v70, 0xffff0000, v70
	v_pk_mul_f32 v[70:71], v[70:71], v[70:71]
	s_mov_b64 s[0:1], 0
	v_pk_fma_f32 v[70:71], v[74:75], v[74:75], v[70:71]
	s_nop 0
	v_add_f32_e32 v49, v57, v70
	v_add_f32_e32 v49, v49, v71
	v_lshlrev_b32_e32 v71, 16, v73
	v_lshlrev_b32_e32 v70, 16, v72
	v_and_b32_e32 v73, 0xffff0000, v73
	v_and_b32_e32 v72, 0xffff0000, v72
	v_pk_mul_f32 v[72:73], v[72:73], v[72:73]
	s_nop 0
	v_pk_fma_f32 v[70:71], v[70:71], v[70:71], v[72:73]
	s_nop 0
	v_add_f32_e32 v49, v49, v70
	v_add_f32_e32 v49, v49, v71

; DEV unsigned cvtpk(float lo, float hi) { f32x2_t v = {lo, hi}; bf16x2_t b = __builtin_convertvector(v, bf16x2_t); return __builtin_bit_cast(unsigned, b); }
; DEV void post_rows(const Params& p, const float* __restrict__ xsrc, const float* __restrict__ g, bool final) {
;     ...
;     for (int c = 0; c < 4; ++c) { const int idx = c * 512 + lane * 8;
;       float xo[8];
;       if (xsrc) { const f32x4 a = *reinterpret_cast<const f32x4*>(xsrc + (size_t)row * DM + idx), b = *reinterpret_cast<const f32x4*>(xsrc + (size_t)row * DM + idx + 4);
; #pragma unroll
;         for (int e = 0; e < 4; ++e) { xo[e] = a[e]; xo[4 + e] = b[e]; } }
;       else { const u32x4 w = *reinterpret_cast<const u32x4*>(xb + (size_t)row * DM + idx);
; #pragma unroll
;         for (int e = 0; e < 4; ++e) { xo[2 * e] = __uint_as_float(w[e] << 16); xo[2 * e + 1] = __uint_as_float(w[e] & 0xffff0000u); } }
;       const f32x4 g0 = *reinterpret_cast<const f32x4*>(g + idx), g1 = *reinterpret_cast<const f32x4*>(g + idx + 4);
;       float xn[8];
; #pragma unroll
;       for (int e = 0; e < 4; ++e) { xn[e] = xo[e] + mv[c * 8 + e] * rm * g0[e]; xn[4 + e] = xo[4 + e] + mv[c * 8 + 4 + e] * rm * g1[e]; }
;       if (final) { *reinterpret_cast<f32x4*>(p.out + (size_t)row * DM + idx) = (f32x4){xn[0], xn[1], xn[2], xn[3]};
;                    *reinterpret_cast<f32x4*>(p.out + (size_t)row * DM + idx + 4) = (f32x4){xn[4], xn[5], xn[6], xn[7]}; }
;       else { const u32x4 w = {cvtpk(xn[0], xn[1]), cvtpk(xn[2], xn[3]), cvtpk(xn[4], xn[5]), cvtpk(xn[6], xn[7])};
;         *reinterpret_cast<u32x4*>(xb + (size_t)row * DM + idx) = w;
; #pragma unroll
;         for (int e = 0; e < 4; ++e) { const float lo = __uint_as_float(w[e] << 16), hi = __uint_as_float(w[e] & 0xffff0000u); sx += lo * lo + hi * hi; } } }
.LBB0_765:
	v_mov_b32_e32 v61, v65
	v_mov_b32_e32 v63, v67
	s_nop 0
	v_pk_mul_f32 v[32:33], v[68:69], v[60:61]
	v_mov_b32_e32 v57, v43
	v_pk_mul_f32 v[34:35], v[68:69], v[62:63]
	v_mov_b32_e32 v59, v51
	s_mov_b64 s[0:1], -1
	s_and_b64 vcc, exec, s[6:7]
	s_waitcnt vmcnt(3)
	v_lshlrev_b32_e32 v36, 16, v124
	v_and_b32_e32 v37, 0xffff0000, v124
	v_pk_fma_f32 v[36:37], v[24:25], v[32:33], v[36:37]
	v_lshlrev_b32_e32 v32, 16, v126
	v_and_b32_e32 v33, 0xffff0000, v126
	v_pk_fma_f32 v[32:33], v[28:29], v[34:35], v[32:33]
	v_pk_mul_f32 v[34:35], v[68:69], v[56:57]
	v_lshlrev_b32_e32 v38, 16, v125
	v_and_b32_e32 v39, 0xffff0000, v125
	v_pk_mul_f32 v[56:57], v[68:69], v[58:59]
	v_pk_fma_f32 v[38:39], v[26:27], v[34:35], v[38:39]
	v_lshlrev_b32_e32 v34, 16, v127
	v_and_b32_e32 v35, 0xffff0000, v127
	v_pk_fma_f32 v[34:35], v[30:31], v[56:57], v[34:35]
	s_cbranch_vccnz .LBB0_768
	v_cvt_pk_bf16_f32 v56, v36, v37
	v_cvt_pk_bf16_f32 v57, v38, v39
	v_cvt_pk_bf16_f32 v58, v32, v33
	v_cvt_pk_bf16_f32 v59, v34, v35
	global_store_dwordx4 v[52:53], v[56:59], off offset:3072
	v_lshlrev_b32_e32 v53, 16, v57
	v_lshlrev_b32_e32 v52, 16, v56
	v_and_b32_e32 v57, 0xffff0000, v57
	v_and_b32_e32 v56, 0xffff0000, v56
	v_pk_mul_f32 v[56:57], v[56:57], v[56:57]
	s_nop 0
	v_pk_fma_f32 v[52:53], v[52:53], v[52:53], v[56:57]
	v_and_b32_e32 v57, 0xffff0000, v59
	v_add_f32_e32 v43, v49, v52
	v_and_b32_e32 v56, 0xffff0000, v58
	v_add_f32_e32 v43, v43, v53
	v_lshlrev_b32_e32 v53, 16, v59
	v_lshlrev_b32_e32 v52, 16, v58
	v_pk_mul_f32 v[56:57], v[56:57], v[56:57]
	s_nop 0
	v_pk_fma_f32 v[52:53], v[52:53], v[52:53], v[56:57]
	s_nop 0
	v_add_f32_e32 v43, v43, v52
	v_add_f32_e32 v43, v43, v53
	s_cbranch_execz .LBB0_769
